# q_b/kv_b tiles: rstd load overlapped with first LDS-DMA (single prologue wait), no store drain at tile top; q_b rope table preloaded at tile start
# baseline (speedup 1.0000x reference)
.LBB0_598:
	s_and_b32 s2, s66, 0x700
	s_or_b32 s34, s2, s63
	s_movk_i32 s2, 0x100
	v_mov_b32 v0, v144
	s_nop 0
	v_readfirstlane_b32 s4, v0
	v_cmp_gt_i32_e32 vcc, s2, v0
	s_barrier
	s_and_saveexec_b64 s[2:3], vcc
	s_cbranch_execz .LBB0_600
	s_waitcnt lgkmcnt(0)
	v_add_u32_e32 v1, s34, v0
	v_add_u32_e32 v2, 0x8000, v1
	v_ashrrev_i32_e32 v3, 31, v2
	v_lshl_add_u64 v[2:3], v[2:3], 2, s[0:1]
	global_load_dword v238, v[2:3], off
.LBB0_600:
	s_or_b64 exec, exec, s[2:3]
	s_lshr_b32 s2, s71, 3
	s_ashr_i32 s3, s4, 6
	s_mul_i32 s5, s34, 0xe00
	s_add_u32 s14, s27, s5
	s_addc_u32 s15, s60, 0
	s_lshl_b32 s8, s2, 8
	s_lshl_b64 s[72:73], s[8:9], 7
	s_add_u32 s72, s61, s72
	s_addc_u32 s73, s62, s73
	s_lshl_b32 s5, s3, 2
	s_waitcnt lgkmcnt(0)
	v_and_b32_e32 v1, 7, v0
	v_bfe_u32 v2, v0, 4, 2
	s_and_b32 s5, s5, 4
	v_bitop3_b32 v1, s5, v1, v2 bitop3:0x36
	v_bfe_u32 v2, v0, 3, 3
	v_lshl_or_b32 v2, s3, 3, v2
	v_ashrrev_i32_e32 v3, 31, v2
	v_mov_b64_e32 v[4:5], s[14:15]
	s_movk_i32 s5, 0xe00
	s_lshl_b32 s80, s3, 10
	v_mad_i64_i32 v[4:5], s[14:15], v2, s5, v[4:5]
	v_lshlrev_b32_e32 v128, 4, v1
	v_lshlrev_b64 v[2:3], 7, v[2:3]
	s_add_i32 s79, s80, 0
	v_lshl_add_u64 v[130:131], v[4:5], 0, v[128:129]
	v_lshl_add_u64 v[2:3], s[72:73], 0, v[2:3]
	s_mov_b32 m0, s79
	s_mov_b64 s[14:15], 0x38000
	s_add_i32 s78, s79, 0x2000
	v_lshl_add_u64 v[132:133], v[2:3], 0, v[128:129]
	global_load_lds_dwordx4 v[130:131], off
	v_lshl_add_u64 v[2:3], v[130:131], 0, s[14:15]
	s_mov_b32 m0, s78
	s_mov_b64 s[14:15], 0x70000
	s_add_i32 s76, s79, 0x4000
	global_load_lds_dwordx4 v[2:3], off
	v_lshl_add_u64 v[2:3], v[130:131], 0, s[14:15]
	s_mov_b32 m0, s76
	s_mov_b64 s[14:15], 0xa8000
	s_add_i32 s77, s79, 0x6000
	global_load_lds_dwordx4 v[2:3], off
	v_lshl_add_u64 v[2:3], v[130:131], 0, s[14:15]
	s_mov_b32 m0, s77
	s_mov_b64 s[14:15], 0x2000
	global_load_lds_dwordx4 v[2:3], off
	s_add_i32 m0, s79, 0x10000
	v_lshl_add_u64 v[2:3], v[132:133], 0, s[14:15]
	global_load_lds_dwordx4 v[132:133], off
	s_add_i32 m0, s79, 0x12000
	s_mov_b64 s[14:15], 0x4000
	global_load_lds_dwordx4 v[2:3], off
	v_lshl_add_u64 v[2:3], v[132:133], 0, s[14:15]
	s_add_i32 m0, s79, 0x14000
	s_mov_b64 s[14:15], 0x6000
	global_load_lds_dwordx4 v[2:3], off
	v_lshl_add_u64 v[2:3], v[132:133], 0, s[14:15]
	s_add_i32 m0, s79, 0x16000
	s_cmp_lt_i32 s3, 4
	global_load_lds_dwordx4 v[2:3], off
	v_cmp_gt_i32_e32 vcc, 0x100, v144
	s_and_saveexec_b64 s[98:99], vcc
	s_cbranch_execz .Lrs_skip3
	s_waitcnt vmcnt(0)
	v_div_scale_f32 v239, s[100:101], s69, s69, v238
	v_rcp_f32_e32 v240, v239
	v_div_scale_f32 v241, vcc, v238, s69, v238
	v_fma_f32 v242, -v239, v240, 1.0
	v_fmac_f32_e32 v240, v242, v240
	v_mul_f32_e32 v242, v241, v240
	v_fma_f32 v243, -v239, v242, v241
	v_fmac_f32_e32 v242, v243, v240
	v_fma_f32 v239, -v239, v242, v241
	v_div_fmas_f32 v239, v239, v240, v242
	v_div_fixup_f32 v238, v239, s69, v238
	v_add_f32_e32 v238, 0x358637bd, v238
	v_mul_f32_e32 v239, 0x4b800000, v238
	v_cmp_gt_f32_e32 vcc, 0x800000, v238
	s_nop 1
	v_cndmask_b32_e32 v238, v238, v239, vcc
	v_rsq_f32_e32 v238, v238
	v_lshl_add_u32 v239, v144, 2, 0
	v_add_u32_e32 v239, 0x20000, v239
	v_mul_f32_e32 v240, 0x45800000, v238
	v_cndmask_b32_e32 v238, v238, v240, vcc
	ds_write_b32 v239, v238
.Lrs_skip3:
	s_or_b64 exec, exec, s[98:99]
	s_cmp_lt_i32 s3, 4
	s_waitcnt vmcnt(0)
	s_barrier
	s_cbranch_scc1 .LBB0_602
	s_barrier
.LBB0_602:
	v_lshrrev_b32_e32 v236, 7, v144
	v_and_b32_e32 v206, 31, v144
	v_lshl_add_u32 v236, v236, 6, v206
	v_add_u32_e32 v236, s34, v236
	v_bfe_u32 v206, v144, 5, 1
	v_lshlrev_b32_e32 v206, 6, v206
	v_lshl_add_u32 v236, v236, 8, v206
	s_add_u32 s100, s6, 0x2000
	s_addc_u32 s101, s7, 0
	global_load_dwordx4 v[206:209], v236, s[6:7] offset:0
	global_load_dwordx4 v[210:213], v236, s[6:7] offset:16
	global_load_dwordx4 v[214:217], v236, s[6:7] offset:32
	global_load_dwordx4 v[218:221], v236, s[6:7] offset:48
	global_load_dwordx4 v[222:225], v236, s[6:7] offset:128
	global_load_dwordx4 v[226:229], v236, s[6:7] offset:144
	global_load_dwordx4 v[230:233], v236, s[6:7] offset:160
	global_load_dwordx2 v[234:235], v236, s[6:7] offset:176
	global_load_dwordx2 v[254:255], v236, s[6:7] offset:184
	global_load_dwordx4 v[238:241], v236, s[100:101] offset:0
	global_load_dwordx4 v[242:245], v236, s[100:101] offset:16
	global_load_dwordx4 v[246:249], v236, s[100:101] offset:32
	global_load_dwordx4 v[250:253], v236, s[100:101] offset:48
	v_and_b32_e32 v162, 63, v0
	s_ashr_i32 s35, s4, 1
	s_andn2_b32 s35, s35, 63
	v_and_b32_e32 v1, 31, v0
	v_lshrrev_b32_e32 v128, 5, v162
	v_lshrrev_b32_e32 v2, 1, v0
	s_and_b32 s4, s3, 1
	v_or_b32_e32 v148, s35, v1
	v_bitop3_b32 v2, v128, v2, 7 bitop3:0x78
	v_lshlrev_b32_e32 v1, 7, v1
	s_mov_b64 s[14:15], 0x80
	v_lshlrev_b32_e32 v149, 4, v2
	v_lshlrev_b32_e32 v163, 7, v148
	v_lshl_or_b32 v188, s4, 14, v1
	v_lshl_add_u64 v[14:15], v[130:131], 0, s[14:15]
	s_mov_b64 s[14:15], 0x38080
	s_mov_b64 s[72:73], 0x32000
	s_add_i32 s84, 0, 0x10000
	s_add_i32 s75, s79, 0x8000
	v_lshl_add_u64 v[28:29], v[130:131], 0, s[14:15]
	s_mov_b64 s[14:15], 0x30000
	v_lshl_add_u64 v[32:33], v[132:133], 0, s[72:73]
	v_add3_u32 v134, 0, v149, v163
	v_add3_u32 v138, s84, v149, v188
	s_mov_b32 m0, s75
	s_add_i32 s72, s79, 0xa000
	s_add_i32 s81, s80, 0x2000
	v_lshl_add_u64 v[30:31], v[132:133], 0, s[14:15]
	s_add_i32 s14, s64, s80
	ds_read_b128 v[2:5], v134
	ds_read_b128 v[16:19], v134 offset:4096
	ds_read_b128 v[6:9], v138
	ds_read_b128 v[10:13], v138 offset:4096
	ds_read_b128 v[20:23], v138 offset:8192
	ds_read_b128 v[24:27], v138 offset:12288
	global_load_lds_dwordx4 v[14:15], off
	s_mov_b32 m0, s72
	s_add_i32 s15, s64, s81
	global_load_lds_dwordx4 v[28:29], off
	s_mov_b32 m0, s14
	s_mov_b64 s[82:83], 0x70080
	global_load_lds_dwordx4 v[30:31], off
	s_mov_b32 m0, s15
	v_bfe_u32 v0, v0, 1, 3
	global_load_lds_dwordx4 v[32:33], off
	v_lshl_add_u64 v[136:137], v[130:131], 0, s[82:83]
	s_mov_b64 s[82:83], 0xa8080
	v_bitop3_b32 v1, v128, v0, 2 bitop3:0x36
	v_lshl_add_u64 v[146:147], v[130:131], 0, s[82:83]
	s_mov_b64 s[82:83], 0x34000
	s_add_i32 s85, s80, 0x4000
	s_add_i32 s88, s80, 0x6000
	v_lshlrev_b32_e32 v189, 4, v1
	v_bitop3_b32 v1, v128, v0, 4 bitop3:0x36
	v_bitop3_b32 v0, v128, v0, 6 bitop3:0x36
	v_lshl_add_u64 v[154:155], v[132:133], 0, s[82:83]
	s_mov_b64 s[82:83], 0x36000
	v_lshlrev_b32_e32 v190, 4, v1
	v_lshlrev_b32_e32 v191, 4, v0
	s_add_i32 s5, s64, s85
	v_lshl_add_u64 v[180:181], v[132:133], 0, s[82:83]
	s_add_i32 s8, s64, s88
	s_barrier
	s_waitcnt lgkmcnt(0)
	s_setprio 3
	s_waitcnt lgkmcnt(0)
	v_mfma_f32_32x32x16_bf16 v[96:111], v[6:9], v[2:5], 0
	v_mfma_f32_32x32x16_bf16 v[112:127], v[10:13], v[2:5], 0
	v_mfma_f32_32x32x16_bf16 v[32:47], v[20:23], v[2:5], 0
	v_mfma_f32_32x32x16_bf16 v[48:63], v[24:27], v[2:5], 0
	v_mfma_f32_32x32x16_bf16 v[64:79], v[6:9], v[16:19], 0
	v_mfma_f32_32x32x16_bf16 v[80:95], v[10:13], v[16:19], 0
	v_mfma_f32_32x32x16_bf16 v[0:15], v[20:23], v[16:19], 0
	v_mfma_f32_32x32x16_bf16 v[16:31], v[24:27], v[16:19], 0
	s_setprio 0
	s_add_i32 s73, s79, 0xc000
	s_barrier
	v_add3_u32 v135, 0, v189, v163
	v_add3_u32 v139, s84, v189, v188
	s_mov_b32 m0, s73
	s_add_i32 s74, s79, 0xe000
	ds_read_b128 v[140:143], v135
	ds_read_b128 v[150:153], v135 offset:4096
	ds_read_b128 v[164:167], v139
	ds_read_b128 v[168:171], v139 offset:4096
	ds_read_b128 v[172:175], v139 offset:8192
	ds_read_b128 v[176:179], v139 offset:12288
	global_load_lds_dwordx4 v[136:137], off
	s_mov_b32 m0, s74
	s_nop 0
	global_load_lds_dwordx4 v[146:147], off
	s_mov_b32 m0, s5
	s_nop 0
	global_load_lds_dwordx4 v[154:155], off
	s_mov_b32 m0, s8
	s_nop 0
	global_load_lds_dwordx4 v[180:181], off
	s_barrier
	s_waitcnt lgkmcnt(0)
	s_setprio 3
	s_waitcnt lgkmcnt(0)
	v_mfma_f32_32x32x16_bf16 v[96:111], v[164:167], v[140:143], v[96:111]
	v_mfma_f32_32x32x16_bf16 v[112:127], v[168:171], v[140:143], v[112:127]
	v_mfma_f32_32x32x16_bf16 v[32:47], v[172:175], v[140:143], v[32:47]
	v_mfma_f32_32x32x16_bf16 v[48:63], v[176:179], v[140:143], v[48:63]
	v_mfma_f32_32x32x16_bf16 v[64:79], v[164:167], v[150:153], v[64:79]
	v_mfma_f32_32x32x16_bf16 v[80:95], v[168:171], v[150:153], v[80:95]
	v_mfma_f32_32x32x16_bf16 v[0:15], v[172:175], v[150:153], v[0:15]
	v_mfma_f32_32x32x16_bf16 v[16:31], v[176:179], v[150:153], v[16:31]
	s_setprio 0
	s_barrier
	v_add3_u32 v136, 0, v190, v163
	v_add3_u32 v140, s84, v190, v188
	ds_read_b128 v[150:153], v136
	ds_read_b128 v[164:167], v136 offset:4096
	ds_read_b128 v[168:171], v140
	ds_read_b128 v[172:175], v140 offset:4096
	ds_read_b128 v[176:179], v140 offset:8192
	ds_read_b128 v[180:183], v140 offset:12288
	s_barrier
	s_waitcnt lgkmcnt(0)
	s_setprio 3
	s_waitcnt lgkmcnt(0)
	v_mfma_f32_32x32x16_bf16 v[96:111], v[168:171], v[150:153], v[96:111]
	v_mfma_f32_32x32x16_bf16 v[112:127], v[172:175], v[150:153], v[112:127]
	v_mfma_f32_32x32x16_bf16 v[32:47], v[176:179], v[150:153], v[32:47]
	v_mfma_f32_32x32x16_bf16 v[48:63], v[180:183], v[150:153], v[48:63]
	v_mfma_f32_32x32x16_bf16 v[64:79], v[168:171], v[164:167], v[64:79]
	v_mfma_f32_32x32x16_bf16 v[80:95], v[172:175], v[164:167], v[80:95]
	v_mfma_f32_32x32x16_bf16 v[0:15], v[176:179], v[164:167], v[0:15]
	v_mfma_f32_32x32x16_bf16 v[16:31], v[180:183], v[164:167], v[16:31]
	s_setprio 0
	s_barrier
	v_add3_u32 v137, 0, v191, v163
	v_add3_u32 v141, s84, v191, v188
	ds_read_b128 v[150:153], v137
	ds_read_b128 v[164:167], v137 offset:4096
	ds_read_b128 v[168:171], v141
	ds_read_b128 v[172:175], v141 offset:4096
	ds_read_b128 v[176:179], v141 offset:8192
	ds_read_b128 v[180:183], v141 offset:12288
	s_waitcnt vmcnt(0)
	s_barrier
	s_waitcnt lgkmcnt(0)
	s_setprio 3
	s_waitcnt lgkmcnt(0)
	v_mfma_f32_32x32x16_bf16 v[96:111], v[168:171], v[150:153], v[96:111]
	v_mfma_f32_32x32x16_bf16 v[112:127], v[172:175], v[150:153], v[112:127]
	v_mfma_f32_32x32x16_bf16 v[32:47], v[176:179], v[150:153], v[32:47]
	v_mfma_f32_32x32x16_bf16 v[48:63], v[180:183], v[150:153], v[48:63]
	v_mfma_f32_32x32x16_bf16 v[64:79], v[168:171], v[164:167], v[64:79]
	v_mfma_f32_32x32x16_bf16 v[80:95], v[172:175], v[164:167], v[80:95]
	v_mfma_f32_32x32x16_bf16 v[0:15], v[176:179], v[164:167], v[0:15]
	v_mfma_f32_32x32x16_bf16 v[16:31], v[180:183], v[164:167], v[16:31]
	s_setprio 0
	s_mov_b64 s[82:83], 0x100
	v_lshl_add_u64 v[146:147], v[130:131], 0, s[82:83]
	s_mov_b64 s[82:83], 0x38100
	v_lshl_add_u64 v[154:155], v[130:131], 0, s[82:83]
	s_mov_b64 s[82:83], 0x60000
	s_mov_b32 m0, s79
	s_barrier
	v_lshl_add_u64 v[184:185], v[132:133], 0, s[82:83]
	s_mov_b64 s[82:83], 0x62000
	v_add3_u32 v142, s64, v149, v188
	v_lshl_add_u64 v[186:187], v[132:133], 0, s[82:83]
	ds_read_b128 v[150:153], v134 offset:32768
	ds_read_b128 v[164:167], v134 offset:36864
	ds_read_b128 v[168:171], v142
	ds_read_b128 v[172:175], v142 offset:4096
	ds_read_b128 v[176:179], v142 offset:8192
	ds_read_b128 v[180:183], v142 offset:12288
	global_load_lds_dwordx4 v[146:147], off
	s_mov_b32 m0, s78
	s_add_i32 s83, s84, s80
	s_add_i32 s82, s84, s81
	global_load_lds_dwordx4 v[154:155], off
	s_mov_b32 m0, s83
	s_mov_b64 s[80:81], 0x70100
	global_load_lds_dwordx4 v[184:185], off
	s_mov_b32 m0, s82
	v_lshl_add_u64 v[146:147], v[130:131], 0, s[80:81]
	global_load_lds_dwordx4 v[186:187], off
	s_mov_b64 s[80:81], 0xa8100
	v_lshl_add_u64 v[154:155], v[130:131], 0, s[80:81]
	s_mov_b64 s[80:81], 0x64000
	v_lshl_add_u64 v[184:185], v[132:133], 0, s[80:81]
	s_add_i32 s80, s84, s85
	v_lshl_add_u64 v[186:187], v[132:133], 0, s[86:87]
	s_add_i32 s81, s84, s88
	s_barrier
	s_waitcnt lgkmcnt(0)
	s_setprio 3
	s_waitcnt lgkmcnt(0)
	v_mfma_f32_32x32x16_bf16 v[96:111], v[168:171], v[150:153], v[96:111]
	v_mfma_f32_32x32x16_bf16 v[112:127], v[172:175], v[150:153], v[112:127]
	v_mfma_f32_32x32x16_bf16 v[32:47], v[176:179], v[150:153], v[32:47]
	v_mfma_f32_32x32x16_bf16 v[48:63], v[180:183], v[150:153], v[48:63]
	v_mfma_f32_32x32x16_bf16 v[64:79], v[168:171], v[164:167], v[64:79]
	v_mfma_f32_32x32x16_bf16 v[80:95], v[172:175], v[164:167], v[80:95]
	v_mfma_f32_32x32x16_bf16 v[0:15], v[176:179], v[164:167], v[0:15]
	v_mfma_f32_32x32x16_bf16 v[16:31], v[180:183], v[164:167], v[16:31]
	s_setprio 0
	s_barrier
	v_add3_u32 v143, s64, v189, v188
	s_mov_b32 m0, s76
	ds_read_b128 v[150:153], v135 offset:32768
	ds_read_b128 v[164:167], v135 offset:36864
	ds_read_b128 v[168:171], v143
	ds_read_b128 v[172:175], v143 offset:4096
	ds_read_b128 v[176:179], v143 offset:8192
	ds_read_b128 v[180:183], v143 offset:12288
	global_load_lds_dwordx4 v[146:147], off
	s_mov_b32 m0, s77
	s_nop 0
	global_load_lds_dwordx4 v[154:155], off
	s_mov_b32 m0, s80
	s_nop 0
	global_load_lds_dwordx4 v[184:185], off
	s_mov_b32 m0, s81
	s_nop 0
	global_load_lds_dwordx4 v[186:187], off
	s_barrier
	s_waitcnt lgkmcnt(0)
	s_setprio 3
	s_waitcnt lgkmcnt(0)
	v_mfma_f32_32x32x16_bf16 v[96:111], v[168:171], v[150:153], v[96:111]
	v_mfma_f32_32x32x16_bf16 v[112:127], v[172:175], v[150:153], v[112:127]
	v_mfma_f32_32x32x16_bf16 v[32:47], v[176:179], v[150:153], v[32:47]
	v_mfma_f32_32x32x16_bf16 v[48:63], v[180:183], v[150:153], v[48:63]
	v_mfma_f32_32x32x16_bf16 v[64:79], v[168:171], v[164:167], v[64:79]
	v_mfma_f32_32x32x16_bf16 v[80:95], v[172:175], v[164:167], v[80:95]
	v_mfma_f32_32x32x16_bf16 v[0:15], v[176:179], v[164:167], v[0:15]
	v_mfma_f32_32x32x16_bf16 v[16:31], v[180:183], v[164:167], v[16:31]
	s_setprio 0
	s_barrier
	v_add3_u32 v146, s64, v190, v188
	ds_read_b128 v[150:153], v136 offset:32768
	ds_read_b128 v[164:167], v136 offset:36864
	ds_read_b128 v[168:171], v146
	ds_read_b128 v[172:175], v146 offset:4096
	ds_read_b128 v[176:179], v146 offset:8192
	ds_read_b128 v[180:183], v146 offset:12288
	s_barrier
	s_waitcnt lgkmcnt(0)
	s_setprio 3
	s_waitcnt lgkmcnt(0)
	v_mfma_f32_32x32x16_bf16 v[96:111], v[168:171], v[150:153], v[96:111]
	v_mfma_f32_32x32x16_bf16 v[112:127], v[172:175], v[150:153], v[112:127]
	v_mfma_f32_32x32x16_bf16 v[32:47], v[176:179], v[150:153], v[32:47]
	v_mfma_f32_32x32x16_bf16 v[48:63], v[180:183], v[150:153], v[48:63]
	v_mfma_f32_32x32x16_bf16 v[64:79], v[168:171], v[164:167], v[64:79]
	v_mfma_f32_32x32x16_bf16 v[80:95], v[172:175], v[164:167], v[80:95]
	v_mfma_f32_32x32x16_bf16 v[0:15], v[176:179], v[164:167], v[0:15]
	v_mfma_f32_32x32x16_bf16 v[16:31], v[180:183], v[164:167], v[16:31]
	s_setprio 0
	s_barrier
	v_add3_u32 v147, s64, v191, v188
	ds_read_b128 v[150:153], v137 offset:32768
	ds_read_b128 v[164:167], v137 offset:36864
	ds_read_b128 v[168:171], v147
	ds_read_b128 v[172:175], v147 offset:4096
	ds_read_b128 v[176:179], v147 offset:8192
	ds_read_b128 v[180:183], v147 offset:12288
	s_waitcnt vmcnt(0)
	s_barrier
	s_waitcnt lgkmcnt(0)
	s_setprio 3
	s_waitcnt lgkmcnt(0)
	v_mfma_f32_32x32x16_bf16 v[96:111], v[168:171], v[150:153], v[96:111]
	v_mfma_f32_32x32x16_bf16 v[112:127], v[172:175], v[150:153], v[112:127]
	v_mfma_f32_32x32x16_bf16 v[32:47], v[176:179], v[150:153], v[32:47]
	v_mfma_f32_32x32x16_bf16 v[48:63], v[180:183], v[150:153], v[48:63]
	v_mfma_f32_32x32x16_bf16 v[64:79], v[168:171], v[164:167], v[64:79]
	v_mfma_f32_32x32x16_bf16 v[80:95], v[172:175], v[164:167], v[80:95]
	v_mfma_f32_32x32x16_bf16 v[0:15], v[176:179], v[164:167], v[0:15]
	v_mfma_f32_32x32x16_bf16 v[16:31], v[180:183], v[164:167], v[16:31]
	s_setprio 0
	s_mov_b64 s[84:85], 0x180
	s_mov_b32 m0, s75
	s_barrier
	v_lshl_add_u64 v[154:155], v[130:131], 0, s[84:85]
	s_mov_b64 s[84:85], 0x38180
	v_lshl_add_u64 v[184:185], v[130:131], 0, s[84:85]
	ds_read_b128 v[150:153], v134
	ds_read_b128 v[164:167], v134 offset:4096
	ds_read_b128 v[168:171], v138
	ds_read_b128 v[172:175], v138 offset:4096
	ds_read_b128 v[176:179], v138 offset:8192
	ds_read_b128 v[180:183], v138 offset:12288
	global_load_lds_dwordx4 v[154:155], off
	s_mov_b32 m0, s72
	v_lshl_add_u64 v[186:187], v[132:133], 0, s[10:11]
	global_load_lds_dwordx4 v[184:185], off
	s_mov_b32 m0, s14
	v_lshl_add_u64 v[188:189], v[132:133], 0, s[12:13]
	global_load_lds_dwordx4 v[186:187], off
	s_mov_b32 m0, s15
	s_mov_b64 s[84:85], 0x70180
	global_load_lds_dwordx4 v[188:189], off
	v_lshl_add_u64 v[154:155], v[130:131], 0, s[84:85]
	s_mov_b64 s[84:85], 0xa8180
	v_lshl_add_u64 v[184:185], v[130:131], 0, s[84:85]
	s_mov_b64 s[84:85], 0x94000
	v_lshl_add_u64 v[186:187], v[132:133], 0, s[84:85]
	s_mov_b64 s[84:85], 0x96000
	v_lshl_add_u64 v[188:189], v[132:133], 0, s[84:85]
	s_barrier
	s_waitcnt lgkmcnt(0)
	s_setprio 3
	s_waitcnt lgkmcnt(0)
	v_mfma_f32_32x32x16_bf16 v[96:111], v[168:171], v[150:153], v[96:111]
	v_mfma_f32_32x32x16_bf16 v[112:127], v[172:175], v[150:153], v[112:127]
	v_mfma_f32_32x32x16_bf16 v[32:47], v[176:179], v[150:153], v[32:47]
	v_mfma_f32_32x32x16_bf16 v[48:63], v[180:183], v[150:153], v[48:63]
	v_mfma_f32_32x32x16_bf16 v[64:79], v[168:171], v[164:167], v[64:79]
	v_mfma_f32_32x32x16_bf16 v[80:95], v[172:175], v[164:167], v[80:95]
	v_mfma_f32_32x32x16_bf16 v[0:15], v[176:179], v[164:167], v[0:15]
	v_mfma_f32_32x32x16_bf16 v[16:31], v[180:183], v[164:167], v[16:31]
	s_setprio 0
	s_barrier
	s_mov_b32 m0, s73
	ds_read_b128 v[150:153], v135
	ds_read_b128 v[164:167], v135 offset:4096
	ds_read_b128 v[168:171], v139
	ds_read_b128 v[172:175], v139 offset:4096
	ds_read_b128 v[176:179], v139 offset:8192
	ds_read_b128 v[180:183], v139 offset:12288
	global_load_lds_dwordx4 v[154:155], off
	s_mov_b32 m0, s74
	s_nop 0
	global_load_lds_dwordx4 v[184:185], off
	s_mov_b32 m0, s5
	s_nop 0
	global_load_lds_dwordx4 v[186:187], off
	s_mov_b32 m0, s8
	s_nop 0
	global_load_lds_dwordx4 v[188:189], off
	s_barrier
	s_waitcnt lgkmcnt(0)
	s_setprio 3
	s_waitcnt lgkmcnt(0)
	v_mfma_f32_32x32x16_bf16 v[96:111], v[168:171], v[150:153], v[96:111]
	v_mfma_f32_32x32x16_bf16 v[112:127], v[172:175], v[150:153], v[112:127]
	v_mfma_f32_32x32x16_bf16 v[32:47], v[176:179], v[150:153], v[32:47]
	v_mfma_f32_32x32x16_bf16 v[48:63], v[180:183], v[150:153], v[48:63]
	v_mfma_f32_32x32x16_bf16 v[64:79], v[168:171], v[164:167], v[64:79]
	v_mfma_f32_32x32x16_bf16 v[80:95], v[172:175], v[164:167], v[80:95]
	v_mfma_f32_32x32x16_bf16 v[0:15], v[176:179], v[164:167], v[0:15]
	v_mfma_f32_32x32x16_bf16 v[16:31], v[180:183], v[164:167], v[16:31]
	s_setprio 0
	s_barrier
	ds_read_b128 v[150:153], v136
	ds_read_b128 v[164:167], v136 offset:4096
	ds_read_b128 v[168:171], v140
	ds_read_b128 v[172:175], v140 offset:4096
	ds_read_b128 v[176:179], v140 offset:8192
	ds_read_b128 v[180:183], v140 offset:12288
	s_barrier
	s_waitcnt lgkmcnt(0)
	s_setprio 3
	s_waitcnt lgkmcnt(0)
	v_mfma_f32_32x32x16_bf16 v[96:111], v[168:171], v[150:153], v[96:111]
	v_mfma_f32_32x32x16_bf16 v[112:127], v[172:175], v[150:153], v[112:127]
	v_mfma_f32_32x32x16_bf16 v[32:47], v[176:179], v[150:153], v[32:47]
	v_mfma_f32_32x32x16_bf16 v[48:63], v[180:183], v[150:153], v[48:63]
	v_mfma_f32_32x32x16_bf16 v[64:79], v[168:171], v[164:167], v[64:79]
	v_mfma_f32_32x32x16_bf16 v[80:95], v[172:175], v[164:167], v[80:95]
	v_mfma_f32_32x32x16_bf16 v[0:15], v[176:179], v[164:167], v[0:15]
	v_mfma_f32_32x32x16_bf16 v[16:31], v[180:183], v[164:167], v[16:31]
	s_setprio 0
	s_barrier
	ds_read_b128 v[150:153], v137
	ds_read_b128 v[164:167], v137 offset:4096
	ds_read_b128 v[168:171], v141
	ds_read_b128 v[172:175], v141 offset:4096
	ds_read_b128 v[176:179], v141 offset:8192
	ds_read_b128 v[180:183], v141 offset:12288
	s_waitcnt vmcnt(0)
	s_barrier
	s_waitcnt lgkmcnt(0)
	s_setprio 3
	s_waitcnt lgkmcnt(0)
	v_mfma_f32_32x32x16_bf16 v[96:111], v[168:171], v[150:153], v[96:111]
	v_mfma_f32_32x32x16_bf16 v[112:127], v[172:175], v[150:153], v[112:127]
	v_mfma_f32_32x32x16_bf16 v[32:47], v[176:179], v[150:153], v[32:47]
	v_mfma_f32_32x32x16_bf16 v[48:63], v[180:183], v[150:153], v[48:63]
	v_mfma_f32_32x32x16_bf16 v[64:79], v[168:171], v[164:167], v[64:79]
	v_mfma_f32_32x32x16_bf16 v[80:95], v[172:175], v[164:167], v[80:95]
	v_mfma_f32_32x32x16_bf16 v[0:15], v[176:179], v[164:167], v[0:15]
	v_mfma_f32_32x32x16_bf16 v[16:31], v[180:183], v[164:167], v[16:31]
	s_setprio 0
	s_mov_b32 m0, s79
	s_barrier
	v_lshl_add_u64 v[154:155], v[130:131], 0, s[36:37]
	v_lshl_add_u64 v[184:185], v[130:131], 0, s[38:39]
	ds_read_b128 v[150:153], v134 offset:32768
	ds_read_b128 v[164:167], v134 offset:36864
	ds_read_b128 v[168:171], v142
	ds_read_b128 v[172:175], v142 offset:4096
	ds_read_b128 v[176:179], v142 offset:8192
	ds_read_b128 v[180:183], v142 offset:12288
	global_load_lds_dwordx4 v[154:155], off
	s_mov_b32 m0, s78
	v_lshl_add_u64 v[186:187], v[132:133], 0, s[40:41]
	global_load_lds_dwordx4 v[184:185], off
	s_mov_b32 m0, s83
	v_lshl_add_u64 v[188:189], v[132:133], 0, s[42:43]
	global_load_lds_dwordx4 v[186:187], off
	s_mov_b32 m0, s82
	v_lshl_add_u64 v[154:155], v[130:131], 0, s[16:17]
	global_load_lds_dwordx4 v[188:189], off
	v_lshl_add_u64 v[184:185], v[130:131], 0, s[18:19]
	v_lshl_add_u64 v[186:187], v[132:133], 0, s[20:21]
	v_lshl_add_u64 v[188:189], v[132:133], 0, s[22:23]
	s_barrier
	s_waitcnt lgkmcnt(0)
	s_setprio 3
	s_waitcnt lgkmcnt(0)
	v_mfma_f32_32x32x16_bf16 v[96:111], v[168:171], v[150:153], v[96:111]
	v_mfma_f32_32x32x16_bf16 v[112:127], v[172:175], v[150:153], v[112:127]
	v_mfma_f32_32x32x16_bf16 v[32:47], v[176:179], v[150:153], v[32:47]
	v_mfma_f32_32x32x16_bf16 v[48:63], v[180:183], v[150:153], v[48:63]
	v_mfma_f32_32x32x16_bf16 v[64:79], v[168:171], v[164:167], v[64:79]
	v_mfma_f32_32x32x16_bf16 v[80:95], v[172:175], v[164:167], v[80:95]
	v_mfma_f32_32x32x16_bf16 v[0:15], v[176:179], v[164:167], v[0:15]
	v_mfma_f32_32x32x16_bf16 v[16:31], v[180:183], v[164:167], v[16:31]
	s_setprio 0
	s_barrier
	s_mov_b32 m0, s76
	ds_read_b128 v[150:153], v135 offset:32768
	ds_read_b128 v[164:167], v135 offset:36864
	ds_read_b128 v[168:171], v143
	ds_read_b128 v[172:175], v143 offset:4096
	ds_read_b128 v[176:179], v143 offset:8192
	ds_read_b128 v[180:183], v143 offset:12288
	global_load_lds_dwordx4 v[154:155], off
	s_mov_b32 m0, s77
	s_nop 0
	global_load_lds_dwordx4 v[184:185], off
	s_mov_b32 m0, s80
	s_nop 0
	global_load_lds_dwordx4 v[186:187], off
	s_mov_b32 m0, s81
	s_nop 0
	global_load_lds_dwordx4 v[188:189], off
	s_barrier
	s_waitcnt lgkmcnt(0)
	s_setprio 3
	s_waitcnt lgkmcnt(0)
	v_mfma_f32_32x32x16_bf16 v[96:111], v[168:171], v[150:153], v[96:111]
	v_mfma_f32_32x32x16_bf16 v[112:127], v[172:175], v[150:153], v[112:127]
	v_mfma_f32_32x32x16_bf16 v[32:47], v[176:179], v[150:153], v[32:47]
	v_mfma_f32_32x32x16_bf16 v[48:63], v[180:183], v[150:153], v[48:63]
	v_mfma_f32_32x32x16_bf16 v[64:79], v[168:171], v[164:167], v[64:79]
	v_mfma_f32_32x32x16_bf16 v[80:95], v[172:175], v[164:167], v[80:95]
	v_mfma_f32_32x32x16_bf16 v[0:15], v[176:179], v[164:167], v[0:15]
	v_mfma_f32_32x32x16_bf16 v[16:31], v[180:183], v[164:167], v[16:31]
	s_setprio 0
	s_barrier
	ds_read_b128 v[150:153], v136 offset:32768
	ds_read_b128 v[164:167], v136 offset:36864
	ds_read_b128 v[168:171], v146
	ds_read_b128 v[172:175], v146 offset:4096
	ds_read_b128 v[176:179], v146 offset:8192
	ds_read_b128 v[180:183], v146 offset:12288
	s_barrier
	s_waitcnt lgkmcnt(0)
	s_setprio 3
	s_waitcnt lgkmcnt(0)
	v_mfma_f32_32x32x16_bf16 v[96:111], v[168:171], v[150:153], v[96:111]
	v_mfma_f32_32x32x16_bf16 v[112:127], v[172:175], v[150:153], v[112:127]
	v_mfma_f32_32x32x16_bf16 v[32:47], v[176:179], v[150:153], v[32:47]
	v_mfma_f32_32x32x16_bf16 v[48:63], v[180:183], v[150:153], v[48:63]
	v_mfma_f32_32x32x16_bf16 v[64:79], v[168:171], v[164:167], v[64:79]
	v_mfma_f32_32x32x16_bf16 v[80:95], v[172:175], v[164:167], v[80:95]
	v_mfma_f32_32x32x16_bf16 v[0:15], v[176:179], v[164:167], v[0:15]
	v_mfma_f32_32x32x16_bf16 v[16:31], v[180:183], v[164:167], v[16:31]
	s_setprio 0
	s_barrier
	ds_read_b128 v[150:153], v137 offset:32768
	ds_read_b128 v[164:167], v137 offset:36864
	ds_read_b128 v[168:171], v147
	ds_read_b128 v[172:175], v147 offset:4096
	ds_read_b128 v[176:179], v147 offset:8192
	ds_read_b128 v[180:183], v147 offset:12288
	s_waitcnt vmcnt(0)
	s_barrier
	s_waitcnt lgkmcnt(0)
	s_setprio 3
	s_waitcnt lgkmcnt(0)
	v_mfma_f32_32x32x16_bf16 v[96:111], v[168:171], v[150:153], v[96:111]
	v_mfma_f32_32x32x16_bf16 v[112:127], v[172:175], v[150:153], v[112:127]
	v_mfma_f32_32x32x16_bf16 v[32:47], v[176:179], v[150:153], v[32:47]
	v_mfma_f32_32x32x16_bf16 v[48:63], v[180:183], v[150:153], v[48:63]
	v_mfma_f32_32x32x16_bf16 v[64:79], v[168:171], v[164:167], v[64:79]
	v_mfma_f32_32x32x16_bf16 v[80:95], v[172:175], v[164:167], v[80:95]
	v_mfma_f32_32x32x16_bf16 v[0:15], v[176:179], v[164:167], v[0:15]
	v_mfma_f32_32x32x16_bf16 v[16:31], v[180:183], v[164:167], v[16:31]
	s_setprio 0
	s_mov_b32 m0, s75
	s_barrier
	v_lshl_add_u64 v[154:155], v[130:131], 0, s[52:53]
	v_lshl_add_u64 v[184:185], v[130:131], 0, s[54:55]
	ds_read_b128 v[150:153], v134
	ds_read_b128 v[164:167], v134 offset:4096
	ds_read_b128 v[168:171], v138
	ds_read_b128 v[172:175], v138 offset:4096
	ds_read_b128 v[176:179], v138 offset:8192
	ds_read_b128 v[180:183], v138 offset:12288
	global_load_lds_dwordx4 v[154:155], off
	s_mov_b32 m0, s72
	v_lshl_add_u64 v[186:187], v[132:133], 0, s[56:57]
	global_load_lds_dwordx4 v[184:185], off
	s_mov_b32 m0, s14
	v_lshl_add_u64 v[188:189], v[132:133], 0, s[58:59]
	global_load_lds_dwordx4 v[186:187], off
	s_mov_b32 m0, s15
	v_lshl_add_u64 v[154:155], v[130:131], 0, s[44:45]
	global_load_lds_dwordx4 v[188:189], off
	v_lshl_add_u64 v[184:185], v[130:131], 0, s[46:47]
	v_lshl_add_u64 v[186:187], v[132:133], 0, s[48:49]
	v_lshl_add_u64 v[188:189], v[132:133], 0, s[50:51]
	s_barrier
	s_waitcnt lgkmcnt(0)
	s_setprio 3
	s_waitcnt lgkmcnt(0)
	v_mfma_f32_32x32x16_bf16 v[96:111], v[168:171], v[150:153], v[96:111]
	v_mfma_f32_32x32x16_bf16 v[112:127], v[172:175], v[150:153], v[112:127]
	v_mfma_f32_32x32x16_bf16 v[32:47], v[176:179], v[150:153], v[32:47]
	v_mfma_f32_32x32x16_bf16 v[48:63], v[180:183], v[150:153], v[48:63]
	v_mfma_f32_32x32x16_bf16 v[64:79], v[168:171], v[164:167], v[64:79]
	v_mfma_f32_32x32x16_bf16 v[80:95], v[172:175], v[164:167], v[80:95]
	v_mfma_f32_32x32x16_bf16 v[0:15], v[176:179], v[164:167], v[0:15]
	v_mfma_f32_32x32x16_bf16 v[16:31], v[180:183], v[164:167], v[16:31]
	s_setprio 0
	s_barrier
	s_mov_b32 m0, s73
	ds_read_b128 v[130:133], v135
	ds_read_b128 v[150:153], v135 offset:4096
	ds_read_b128 v[164:167], v139
	ds_read_b128 v[168:171], v139 offset:4096
	ds_read_b128 v[172:175], v139 offset:8192
	ds_read_b128 v[176:179], v139 offset:12288
	global_load_lds_dwordx4 v[154:155], off
	s_mov_b32 m0, s74
	s_nop 0
	global_load_lds_dwordx4 v[184:185], off
	s_mov_b32 m0, s5
	s_nop 0
	global_load_lds_dwordx4 v[186:187], off
	s_mov_b32 m0, s8
	s_nop 0
	global_load_lds_dwordx4 v[188:189], off
	s_barrier
	s_waitcnt lgkmcnt(0)
	s_setprio 3
	s_waitcnt lgkmcnt(0)
	v_mfma_f32_32x32x16_bf16 v[96:111], v[164:167], v[130:133], v[96:111]
	v_mfma_f32_32x32x16_bf16 v[112:127], v[168:171], v[130:133], v[112:127]
	v_mfma_f32_32x32x16_bf16 v[32:47], v[172:175], v[130:133], v[32:47]
	v_mfma_f32_32x32x16_bf16 v[48:63], v[176:179], v[130:133], v[48:63]
	v_mfma_f32_32x32x16_bf16 v[64:79], v[164:167], v[150:153], v[64:79]
	v_mfma_f32_32x32x16_bf16 v[80:95], v[168:171], v[150:153], v[80:95]
	v_mfma_f32_32x32x16_bf16 v[0:15], v[172:175], v[150:153], v[0:15]
	v_mfma_f32_32x32x16_bf16 v[16:31], v[176:179], v[150:153], v[16:31]
	s_setprio 0
	s_barrier
	ds_read_b128 v[130:133], v136
	ds_read_b128 v[150:153], v136 offset:4096
	ds_read_b128 v[164:167], v140
	ds_read_b128 v[168:171], v140 offset:4096
	ds_read_b128 v[172:175], v140 offset:8192
	ds_read_b128 v[176:179], v140 offset:12288
	s_barrier
	s_waitcnt lgkmcnt(0)
	s_setprio 3
	s_waitcnt lgkmcnt(0)
	v_mfma_f32_32x32x16_bf16 v[96:111], v[164:167], v[130:133], v[96:111]
	v_mfma_f32_32x32x16_bf16 v[112:127], v[168:171], v[130:133], v[112:127]
	v_mfma_f32_32x32x16_bf16 v[32:47], v[172:175], v[130:133], v[32:47]
	v_mfma_f32_32x32x16_bf16 v[48:63], v[176:179], v[130:133], v[48:63]
	v_mfma_f32_32x32x16_bf16 v[64:79], v[164:167], v[150:153], v[64:79]
	v_mfma_f32_32x32x16_bf16 v[80:95], v[168:171], v[150:153], v[80:95]
	v_mfma_f32_32x32x16_bf16 v[0:15], v[172:175], v[150:153], v[0:15]
	v_mfma_f32_32x32x16_bf16 v[16:31], v[176:179], v[150:153], v[16:31]
	s_setprio 0
	s_barrier
	ds_read_b128 v[130:133], v137
	ds_read_b128 v[150:153], v137 offset:4096
	ds_read_b128 v[164:167], v141
	ds_read_b128 v[168:171], v141 offset:4096
	ds_read_b128 v[172:175], v141 offset:8192
	ds_read_b128 v[138:141], v141 offset:12288
	s_waitcnt vmcnt(0)
	s_barrier
	s_waitcnt lgkmcnt(0)
	s_setprio 3
	s_waitcnt lgkmcnt(0)
	v_mfma_f32_32x32x16_bf16 v[96:111], v[164:167], v[130:133], v[96:111]
	v_mfma_f32_32x32x16_bf16 v[112:127], v[168:171], v[130:133], v[112:127]
	v_mfma_f32_32x32x16_bf16 v[32:47], v[172:175], v[130:133], v[32:47]
	v_mfma_f32_32x32x16_bf16 v[48:63], v[138:141], v[130:133], v[48:63]
	v_mfma_f32_32x32x16_bf16 v[64:79], v[164:167], v[150:153], v[64:79]
	v_mfma_f32_32x32x16_bf16 v[80:95], v[168:171], v[150:153], v[80:95]
	v_mfma_f32_32x32x16_bf16 v[0:15], v[172:175], v[150:153], v[0:15]
	v_mfma_f32_32x32x16_bf16 v[16:31], v[138:141], v[150:153], v[16:31]
	s_setprio 0
	s_barrier
	ds_read_b128 v[130:133], v134 offset:32768
	ds_read_b128 v[138:141], v134 offset:36864
	ds_read_b128 v[150:153], v142
	ds_read_b128 v[164:167], v142 offset:4096
	ds_read_b128 v[168:171], v142 offset:8192
	ds_read_b128 v[172:175], v142 offset:12288
	s_barrier
	s_waitcnt lgkmcnt(0)
	s_setprio 3
	s_waitcnt lgkmcnt(0)
	v_mfma_f32_32x32x16_bf16 v[96:111], v[150:153], v[130:133], v[96:111]
	v_mfma_f32_32x32x16_bf16 v[112:127], v[164:167], v[130:133], v[112:127]
	v_mfma_f32_32x32x16_bf16 v[32:47], v[168:171], v[130:133], v[32:47]
	v_mfma_f32_32x32x16_bf16 v[48:63], v[172:175], v[130:133], v[48:63]
	v_mfma_f32_32x32x16_bf16 v[64:79], v[150:153], v[138:141], v[64:79]
	v_mfma_f32_32x32x16_bf16 v[80:95], v[164:167], v[138:141], v[80:95]
	v_mfma_f32_32x32x16_bf16 v[0:15], v[168:171], v[138:141], v[0:15]
	v_mfma_f32_32x32x16_bf16 v[16:31], v[172:175], v[138:141], v[16:31]
	s_setprio 0
	s_barrier
	ds_read_b128 v[130:133], v135 offset:32768
	ds_read_b128 v[138:141], v135 offset:36864
	ds_read_b128 v[150:153], v143
	ds_read_b128 v[164:167], v143 offset:4096
	ds_read_b128 v[168:171], v143 offset:8192
	ds_read_b128 v[172:175], v143 offset:12288
	s_barrier
	s_waitcnt lgkmcnt(0)
	s_setprio 3
	s_waitcnt lgkmcnt(0)
	v_mfma_f32_32x32x16_bf16 v[96:111], v[150:153], v[130:133], v[96:111]
	v_mfma_f32_32x32x16_bf16 v[112:127], v[164:167], v[130:133], v[112:127]
	v_mfma_f32_32x32x16_bf16 v[32:47], v[168:171], v[130:133], v[32:47]
	v_mfma_f32_32x32x16_bf16 v[48:63], v[172:175], v[130:133], v[48:63]
	v_mfma_f32_32x32x16_bf16 v[64:79], v[150:153], v[138:141], v[64:79]
	v_mfma_f32_32x32x16_bf16 v[80:95], v[164:167], v[138:141], v[80:95]
	v_mfma_f32_32x32x16_bf16 v[0:15], v[168:171], v[138:141], v[0:15]
	v_mfma_f32_32x32x16_bf16 v[16:31], v[172:175], v[138:141], v[16:31]
	s_setprio 0
	s_barrier
	ds_read_b128 v[130:133], v136 offset:32768
	ds_read_b128 v[138:141], v136 offset:36864
	ds_read_b128 v[150:153], v146
	ds_read_b128 v[164:167], v146 offset:4096
	ds_read_b128 v[168:171], v146 offset:8192
	ds_read_b128 v[172:175], v146 offset:12288
	s_barrier
	s_waitcnt lgkmcnt(0)
	s_setprio 3
	s_waitcnt lgkmcnt(0)
	v_mfma_f32_32x32x16_bf16 v[96:111], v[150:153], v[130:133], v[96:111]
	v_mfma_f32_32x32x16_bf16 v[112:127], v[164:167], v[130:133], v[112:127]
	v_mfma_f32_32x32x16_bf16 v[32:47], v[168:171], v[130:133], v[32:47]
	v_mfma_f32_32x32x16_bf16 v[48:63], v[172:175], v[130:133], v[48:63]
	v_mfma_f32_32x32x16_bf16 v[64:79], v[150:153], v[138:141], v[64:79]
	v_mfma_f32_32x32x16_bf16 v[80:95], v[164:167], v[138:141], v[80:95]
	v_mfma_f32_32x32x16_bf16 v[0:15], v[168:171], v[138:141], v[0:15]
	v_mfma_f32_32x32x16_bf16 v[16:31], v[172:175], v[138:141], v[16:31]
	s_setprio 0
	s_barrier
	ds_read_b128 v[130:133], v137 offset:32768
	ds_read_b128 v[134:137], v137 offset:36864
	ds_read_b128 v[138:141], v147
	ds_read_b128 v[150:153], v147 offset:4096
	ds_read_b128 v[164:167], v147 offset:8192
	ds_read_b128 v[168:171], v147 offset:12288
	s_waitcnt vmcnt(0)
	s_barrier
	s_waitcnt lgkmcnt(0)
	s_setprio 3
	s_waitcnt lgkmcnt(0)
	v_mfma_f32_32x32x16_bf16 v[96:111], v[138:141], v[130:133], v[96:111]
	v_mfma_f32_32x32x16_bf16 v[112:127], v[150:153], v[130:133], v[112:127]
	v_mfma_f32_32x32x16_bf16 v[32:47], v[164:167], v[130:133], v[32:47]
	v_mfma_f32_32x32x16_bf16 v[48:63], v[168:171], v[130:133], v[48:63]
	v_mfma_f32_32x32x16_bf16 v[64:79], v[138:141], v[134:137], v[64:79]
	v_mfma_f32_32x32x16_bf16 v[80:95], v[150:153], v[134:137], v[80:95]
	v_mfma_f32_32x32x16_bf16 v[0:15], v[164:167], v[134:137], v[0:15]
	v_mfma_f32_32x32x16_bf16 v[16:31], v[168:171], v[134:137], v[16:31]
	s_setprio 0
	s_barrier
	s_cmp_gt_i32 s3, 3
	s_cbranch_scc1 .LBB0_604
	s_barrier
.LBB0_604:
	v_lshlrev_b32_e32 v149, 3, v128
	v_lshl_add_u32 v128, v148, 2, 0
	s_lshl_b32 s2, s2, 2
	s_lshl_b32 s3, s4, 1
	v_add_u32_e32 v128, 0x20000, v128
	v_mov_b32 v130, 0
	s_or_b32 s8, s3, s2
	ds_read_b32 v128, v128
	s_and_b32 s2, s8, 0xfe
	s_mulk_i32 s2, 0xab
	s_lshr_b32 s2, s2, 9
	s_mul_i32 s2, s2, 3
	v_add_u32_e32 v140, s34, v148
	s_sub_i32 s2, s8, s2
	s_waitcnt lgkmcnt(0)
	v_mul_f32_e32 v130, 0x3dd53b95, v128
	v_ashrrev_i32_e32 v141, 31, v140
	v_mov_b32_e32 v132, v96
	v_mov_b32_e32 v133, v113
	v_mov_b32_e32 v113, v97
	v_mov_b32_e32 v96, v98
	v_mov_b32_e32 v97, v115
	s_and_b32 s2, s2, 0xff
	v_lshlrev_b64 v[142:143], 5, v[140:141]
	v_pk_mul_f32 v[134:135], v[132:133], v[130:131] op_sel_hi:[1,0]
	v_pk_mul_f32 v[132:133], v[96:97], v[130:131] op_sel_hi:[1,0]
	v_mov_b32_e32 v115, v99
	v_mov_b32_e32 v97, v121
	v_mov_b32_e32 v121, v105
	s_cmp_eq_u32 s2, 2
	v_or_b32_e32 v142, v142, v149
	v_pk_mul_f32 v[136:137], v[114:115], v[130:131] op_sel_hi:[1,0]
	v_mov_b32_e32 v96, v104
	v_pk_mul_f32 v[114:115], v[120:121], v[130:131] op_sel_hi:[1,0]
	v_mul_f32_e32 v120, v106, v130
	v_mov_b32_e32 v106, v123
	s_cselect_b64 s[4:5], -1, 0
	s_cmp_lg_u32 s2, 2
	v_pk_mul_f32 v[138:139], v[112:113], v[130:131] op_sel_hi:[1,0]
	v_pk_mul_f32 v[112:113], v[96:97], v[130:131] op_sel_hi:[1,0]
	v_mul_f32_e32 v122, v122, v130
	v_pk_mul_f32 v[106:107], v[106:107], v[130:131] op_sel_hi:[1,0]
	v_lshl_add_u64 v[96:97], v[142:143], 3, s[6:7]
	s_cbranch_scc1 .LBB0_606
	v_mov_b32_e32 v150, v206
	v_mov_b32_e32 v151, v207
	v_mov_b32_e32 v152, v208
	v_mov_b32_e32 v153, v209
	v_mov_b32_e32 v164, v210
	v_mov_b32_e32 v165, v211
	v_mov_b32_e32 v166, v212
	v_mov_b32_e32 v167, v213
	v_mov_b32_e32 v168, v214
	v_mov_b32_e32 v169, v215
	v_mov_b32_e32 v170, v216
	v_mov_b32_e32 v171, v217
	v_mov_b32_e32 v172, v218
	v_mov_b32_e32 v173, v219
	v_mov_b32_e32 v174, v220
	v_mov_b32_e32 v175, v221
	v_mov_b32_e32 v104, v138
	v_mov_b32_e32 v105, v135
	v_mov_b32_e32 v146, v136
	v_mov_b32_e32 v147, v133
	v_mov_b32_e32 v176, v114
	v_mov_b32_e32 v177, v113
	v_mov_b32_e32 v98, v134
	v_mov_b32_e32 v99, v139
	v_mov_b32_e32 v142, v132
	v_mov_b32_e32 v143, v137
	v_mov_b32_e32 v154, v112
	v_mov_b32_e32 v155, v115
	v_mov_b32_e32 v180, v151
	v_mov_b32_e32 v181, v153
	v_mov_b32_e32 v182, v151
	v_mov_b32_e32 v151, v153
	v_mov_b32_e32 v184, v165
	v_mov_b32_e32 v185, v167
	v_mov_b32_e32 v186, v165
	v_mov_b32_e32 v165, v167
	v_mov_b32_e32 v167, v170
	v_mov_b32_e32 v188, v169
	v_mov_b32_e32 v189, v171
	v_mov_b32_e32 v190, v169
	v_mov_b32_e32 v191, v170
	v_mov_b32_e32 v169, v171
	v_mul_f32_e32 v170, v120, v172
	v_mul_f32_e32 v192, v122, v173
	v_mul_f32_e32 v122, v122, v172
	v_mul_f32_e32 v172, v120, v173
	v_pk_mul_f32 v[120:121], v[106:107], v[174:175] op_sel:[1,0] op_sel_hi:[0,1]
	v_pk_mul_f32 v[106:107], v[106:107], v[174:175]
	v_mov_b32_e32 v178, v150
	v_mov_b32_e32 v179, v152
	v_mov_b32_e32 v183, v152
	v_mov_b32_e32 v152, v164
	v_mov_b32_e32 v153, v166
	v_mov_b32_e32 v187, v166
	v_mov_b32_e32 v166, v168
	v_pk_mul_f32 v[104:105], v[104:105], v[180:181]
	v_pk_mul_f32 v[138:139], v[138:139], v[150:151]
	v_pk_mul_f32 v[146:147], v[146:147], v[184:185]
	v_pk_mul_f32 v[136:137], v[136:137], v[164:165]
	v_pk_mul_f32 v[150:151], v[176:177], v[188:189]
	v_pk_mul_f32 v[114:115], v[114:115], v[168:169]
	v_mov_b32_e32 v171, v120
	v_mov_b32_e32 v193, v121
	v_mov_b32_e32 v123, v106
	v_mov_b32_e32 v173, v107
	v_pk_fma_f32 v[98:99], v[98:99], v[178:179], v[104:105] neg_lo:[0,0,1] neg_hi:[0,0,1]
	v_pk_fma_f32 v[104:105], v[142:143], v[152:153], v[146:147] neg_lo:[0,0,1] neg_hi:[0,0,1]
	v_pk_fma_f32 v[142:143], v[154:155], v[166:167], v[150:151] neg_lo:[0,0,1] neg_hi:[0,0,1]
	v_pk_add_f32 v[120:121], v[170:171], v[192:193] neg_lo:[0,1] neg_hi:[0,1]
	v_pk_fma_f32 v[138:139], v[134:135], v[182:183], v[138:139]
	v_pk_fma_f32 v[136:137], v[132:133], v[186:187], v[136:137]
	v_pk_fma_f32 v[114:115], v[112:113], v[190:191], v[114:115]
	v_pk_add_f32 v[122:123], v[122:123], v[172:173]
	v_mov_b32_e32 v135, v139
	v_mov_b32_e32 v133, v137
	v_mov_b32_e32 v113, v115
	v_mov_b32_e32 v106, v123
	v_mov_b32_e32 v134, v98
	v_mov_b32_e32 v139, v99
	v_mov_b32_e32 v132, v104
	v_mov_b32_e32 v137, v105
	v_mov_b32_e32 v112, v142
	v_mov_b32_e32 v115, v143
	v_mov_b32_e32 v107, v121
.LBB0_606:
	s_lshl_b32 s2, s8, 7
	s_add_u32 s2, s65, s2
	s_addc_u32 s3, s68, 0
	v_lshlrev_b32_e32 v128, 1, v149
	v_lshl_add_u64 v[146:147], s[2:3], 0, v[128:129]
	v_mad_i64_i32 v[104:105], s[2:3], v140, s70, 0
	v_lshl_add_u64 v[98:99], v[104:105], 1, v[146:147]
	v_cvt_pk_bf16_f32 v140, v134, v139
	v_cvt_pk_bf16_f32 v141, v132, v137
	v_cvt_pk_bf16_f32 v142, v112, v115
	v_cvt_pk_bf16_f32 v143, v120, v107
	v_mov_b32_e32 v131, v130
	v_cvt_pk_bf16_f32 v150, v138, v135
	v_cvt_pk_bf16_f32 v151, v136, v133
	v_cvt_pk_bf16_f32 v152, v114, v113
	v_cvt_pk_bf16_f32 v153, v122, v106
	global_store_dwordx4 v[98:99], v[140:143], off
	global_store_dwordx4 v[98:99], v[150:153], off offset:64
	s_andn2_b64 vcc, exec, s[4:5]
	v_mov_b32_e32 v140, v100
	v_mov_b32_e32 v141, v117
	v_mov_b32_e32 v117, v101
	v_mov_b32_e32 v100, v102
	v_mov_b32_e32 v101, v119
	v_pk_mul_f32 v[142:143], v[116:117], v[130:131]
	v_pk_mul_f32 v[116:117], v[100:101], v[130:131]
	v_mov_b32_e32 v119, v103
	v_mov_b32_e32 v100, v108
	v_mov_b32_e32 v101, v125
	v_mov_b32_e32 v125, v109
	v_mul_f32_e32 v108, v110, v130
	v_mov_b32_e32 v110, v127
	v_cndmask_b32_e64 v109, 0, 1, s[4:5]
	v_pk_mul_f32 v[140:141], v[140:141], v[130:131]
	v_pk_mul_f32 v[118:119], v[118:119], v[130:131]
	v_pk_mul_f32 v[100:101], v[100:101], v[130:131]
	v_pk_mul_f32 v[102:103], v[124:125], v[130:131]
	v_mul_f32_e32 v124, v126, v130
	v_cmp_ne_u32_e64 s[2:3], 1, v109
	v_pk_mul_f32 v[110:111], v[110:111], v[130:131]
	s_cbranch_vccnz .LBB0_608
	v_mov_b32_e32 v150, v222
	v_mov_b32_e32 v151, v223
	v_mov_b32_e32 v152, v224
	v_mov_b32_e32 v153, v225
	v_mov_b32_e32 v164, v226
	v_mov_b32_e32 v165, v227
	v_mov_b32_e32 v166, v228
	v_mov_b32_e32 v167, v229
	v_mov_b32_e32 v168, v230
	v_mov_b32_e32 v169, v231
	v_mov_b32_e32 v170, v232
	v_mov_b32_e32 v171, v233
	v_mov_b32_e32 v172, v234
	v_mov_b32_e32 v173, v235
	v_mov_b32_e32 v174, v254
	v_mov_b32_e32 v175, v255
	v_mov_b32_e32 v154, v142
	v_mov_b32_e32 v155, v141
	v_mov_b32_e32 v178, v118
	v_mov_b32_e32 v179, v117
	v_mov_b32_e32 v182, v102
	v_mov_b32_e32 v183, v101
	v_mov_b32_e32 v126, v140
	v_mov_b32_e32 v127, v143
	v_mov_b32_e32 v176, v116
	v_mov_b32_e32 v177, v119
	v_mov_b32_e32 v180, v100
	v_mov_b32_e32 v181, v103
	v_mov_b32_e32 v186, v151
	v_mov_b32_e32 v187, v153
	v_mov_b32_e32 v188, v151
	v_mov_b32_e32 v151, v153
	v_mov_b32_e32 v190, v165
	v_mov_b32_e32 v191, v167
	v_mov_b32_e32 v192, v165
	v_mov_b32_e32 v165, v167
	v_mov_b32_e32 v167, v170
	v_mov_b32_e32 v194, v169
	v_mov_b32_e32 v195, v171
	v_mov_b32_e32 v196, v169
	v_mov_b32_e32 v197, v170
	v_mov_b32_e32 v169, v171
	v_mul_f32_e32 v170, v108, v172
	v_mul_f32_e32 v198, v124, v173
	v_mul_f32_e32 v124, v124, v172
	v_mul_f32_e32 v172, v108, v173
	v_pk_mul_f32 v[108:109], v[110:111], v[174:175] op_sel:[1,0] op_sel_hi:[0,1]
	v_pk_mul_f32 v[110:111], v[110:111], v[174:175]
	v_mov_b32_e32 v184, v150
	v_mov_b32_e32 v185, v152
	v_mov_b32_e32 v189, v152
	v_mov_b32_e32 v152, v164
	v_mov_b32_e32 v153, v166
	v_mov_b32_e32 v193, v166
	v_mov_b32_e32 v166, v168
	v_pk_mul_f32 v[154:155], v[154:155], v[186:187]
	v_pk_mul_f32 v[142:143], v[142:143], v[150:151]
	v_pk_mul_f32 v[150:151], v[178:179], v[190:191]
	v_pk_mul_f32 v[118:119], v[118:119], v[164:165]
	v_pk_mul_f32 v[164:165], v[182:183], v[194:195]
	v_pk_mul_f32 v[102:103], v[102:103], v[168:169]
	v_mov_b32_e32 v171, v108
	v_mov_b32_e32 v199, v109
	v_mov_b32_e32 v125, v110
	v_mov_b32_e32 v173, v111
	v_pk_fma_f32 v[126:127], v[126:127], v[184:185], v[154:155] neg_lo:[0,0,1] neg_hi:[0,0,1]
	v_pk_fma_f32 v[150:151], v[176:177], v[152:153], v[150:151] neg_lo:[0,0,1] neg_hi:[0,0,1]
	v_pk_fma_f32 v[152:153], v[180:181], v[166:167], v[164:165] neg_lo:[0,0,1] neg_hi:[0,0,1]
	v_pk_add_f32 v[108:109], v[170:171], v[198:199] neg_lo:[0,1] neg_hi:[0,1]
	v_pk_fma_f32 v[142:143], v[140:141], v[188:189], v[142:143]
	v_pk_fma_f32 v[118:119], v[116:117], v[192:193], v[118:119]
	v_pk_fma_f32 v[102:103], v[100:101], v[196:197], v[102:103]
	v_pk_add_f32 v[124:125], v[124:125], v[172:173]
	v_mov_b32_e32 v141, v143
	v_mov_b32_e32 v117, v119
	v_mov_b32_e32 v101, v103
	v_mov_b32_e32 v110, v125
	v_mov_b32_e32 v140, v126
	v_mov_b32_e32 v143, v127
	v_mov_b32_e32 v116, v150
	v_mov_b32_e32 v119, v151
	v_mov_b32_e32 v100, v152
	v_mov_b32_e32 v103, v153
	v_mov_b32_e32 v111, v109
.LBB0_608:
	v_or_b32_e32 v109, 32, v148
	v_lshl_add_u32 v121, v109, 2, 0
	v_add_u32_e32 v121, 0x20000, v121
	ds_read_b32 v121, v121
	v_cvt_pk_bf16_f32 v150, v140, v143
	v_cvt_pk_bf16_f32 v151, v116, v119
	v_cvt_pk_bf16_f32 v152, v100, v103
	v_cvt_pk_bf16_f32 v153, v108, v111
	v_cvt_pk_bf16_f32 v164, v142, v141
	v_cvt_pk_bf16_f32 v165, v118, v117
	v_cvt_pk_bf16_f32 v166, v102, v101
	v_cvt_pk_bf16_f32 v167, v124, v110
	global_store_dwordx4 v[98:99], v[150:153], off offset:32
	global_store_dwordx4 v[98:99], v[164:167], off offset:96
	s_waitcnt lgkmcnt(0)
	v_mul_f32_e32 v98, 0x3dd53b95, v121
	v_add_u32_e32 v152, s34, v109
	v_ashrrev_i32_e32 v153, 31, v152
	v_lshlrev_b64 v[154:155], 5, v[152:153]
	v_mov_b32_e32 v126, v64
	v_mov_b32_e32 v127, v81
	v_mov_b32_e32 v81, v65
	v_mov_b32_e32 v64, v66
	v_mov_b32_e32 v65, v83
	v_or_b32_e32 v154, v154, v149
	v_pk_mul_f32 v[148:149], v[126:127], v[98:99] op_sel_hi:[1,0]
	v_pk_mul_f32 v[126:127], v[64:65], v[98:99] op_sel_hi:[1,0]
	v_mov_b32_e32 v65, v89
	v_mov_b32_e32 v89, v73
	v_mov_b32_e32 v83, v67
	v_mov_b32_e32 v64, v72
	v_pk_mul_f32 v[72:73], v[88:89], v[98:99] op_sel_hi:[1,0]
	v_mul_f32_e32 v88, v74, v98
	v_mov_b32_e32 v74, v91
	v_pk_mul_f32 v[150:151], v[80:81], v[98:99] op_sel_hi:[1,0]
	v_pk_mul_f32 v[82:83], v[82:83], v[98:99] op_sel_hi:[1,0]
	v_pk_mul_f32 v[80:81], v[64:65], v[98:99] op_sel_hi:[1,0]
	v_mul_f32_e32 v90, v90, v98
	v_pk_mul_f32 v[74:75], v[74:75], v[98:99] op_sel_hi:[1,0]
	s_and_b64 vcc, exec, s[2:3]
	v_lshl_add_u64 v[64:65], v[154:155], 3, s[6:7]
	s_cbranch_vccnz .LBB0_610
	v_mov_b32_e32 v164, v238
	v_mov_b32_e32 v165, v239
	v_mov_b32_e32 v166, v240
	v_mov_b32_e32 v167, v241
	v_mov_b32_e32 v168, v242
	v_mov_b32_e32 v169, v243
	v_mov_b32_e32 v170, v244
	v_mov_b32_e32 v171, v245
	v_mov_b32_e32 v172, v246
	v_mov_b32_e32 v173, v247
	v_mov_b32_e32 v174, v248
	v_mov_b32_e32 v175, v249
	v_mov_b32_e32 v176, v250
	v_mov_b32_e32 v177, v251
	v_mov_b32_e32 v178, v252
	v_mov_b32_e32 v179, v253
	v_mov_b32_e32 v154, v150
	v_mov_b32_e32 v155, v149
	v_mov_b32_e32 v182, v82
	v_mov_b32_e32 v183, v127
	v_mov_b32_e32 v186, v72
	v_mov_b32_e32 v187, v81
	v_mov_b32_e32 v66, v148
	v_mov_b32_e32 v67, v151
	v_mov_b32_e32 v180, v126
	v_mov_b32_e32 v181, v83
	v_mov_b32_e32 v184, v80
	v_mov_b32_e32 v185, v73
	v_mov_b32_e32 v190, v165
	v_mov_b32_e32 v191, v167
	v_mov_b32_e32 v192, v165
	v_mov_b32_e32 v165, v167
	v_mov_b32_e32 v194, v169
	v_mov_b32_e32 v195, v171
	v_mov_b32_e32 v196, v169
	v_mov_b32_e32 v169, v171
	v_mov_b32_e32 v171, v174
	v_mov_b32_e32 v198, v173
	v_mov_b32_e32 v199, v175
	v_mov_b32_e32 v200, v173
	v_mov_b32_e32 v201, v174
	v_mov_b32_e32 v173, v175
	v_mul_f32_e32 v174, v88, v176
	v_mul_f32_e32 v202, v90, v177
	v_mul_f32_e32 v90, v90, v176
	v_mul_f32_e32 v176, v88, v177
	v_pk_mul_f32 v[88:89], v[74:75], v[178:179] op_sel:[1,0] op_sel_hi:[0,1]
	v_pk_mul_f32 v[74:75], v[74:75], v[178:179]
	v_mov_b32_e32 v188, v164
	v_mov_b32_e32 v189, v166
	v_mov_b32_e32 v193, v166
	v_mov_b32_e32 v166, v168
	v_mov_b32_e32 v167, v170
	v_mov_b32_e32 v197, v170
	v_mov_b32_e32 v170, v172
	v_pk_mul_f32 v[154:155], v[154:155], v[190:191]
	v_pk_mul_f32 v[150:151], v[150:151], v[164:165]
	v_pk_mul_f32 v[164:165], v[182:183], v[194:195]
	v_pk_mul_f32 v[82:83], v[82:83], v[168:169]
	v_pk_mul_f32 v[168:169], v[186:187], v[198:199]
	v_pk_mul_f32 v[72:73], v[72:73], v[172:173]
	v_mov_b32_e32 v175, v88
	v_mov_b32_e32 v203, v89
	v_mov_b32_e32 v91, v74
	v_mov_b32_e32 v177, v75
	v_pk_fma_f32 v[66:67], v[66:67], v[188:189], v[154:155] neg_lo:[0,0,1] neg_hi:[0,0,1]
	v_pk_fma_f32 v[154:155], v[180:181], v[166:167], v[164:165] neg_lo:[0,0,1] neg_hi:[0,0,1]
	v_pk_fma_f32 v[164:165], v[184:185], v[170:171], v[168:169] neg_lo:[0,0,1] neg_hi:[0,0,1]
	v_pk_add_f32 v[88:89], v[174:175], v[202:203] neg_lo:[0,1] neg_hi:[0,1]
	v_pk_fma_f32 v[150:151], v[148:149], v[192:193], v[150:151]
	v_pk_fma_f32 v[82:83], v[126:127], v[196:197], v[82:83]
	v_pk_fma_f32 v[72:73], v[80:81], v[200:201], v[72:73]
	v_pk_add_f32 v[90:91], v[90:91], v[176:177]
	v_mov_b32_e32 v149, v151
	v_mov_b32_e32 v127, v83
	v_mov_b32_e32 v81, v73
	v_mov_b32_e32 v74, v91
	v_mov_b32_e32 v148, v66
	v_mov_b32_e32 v151, v67
	v_mov_b32_e32 v126, v154
	v_mov_b32_e32 v83, v155
	v_mov_b32_e32 v80, v164
	v_mov_b32_e32 v73, v165
	v_mov_b32_e32 v75, v89

.LBB0_614:
	s_or_b64 exec, exec, s[4:5]
	s_or_b32 s4, s8, 1
	s_and_b32 s5, s4, 0xff
	s_mulk_i32 s5, 0xab
	s_lshr_b32 s5, s5, 9
	s_mul_i32 s5, s5, 3
	s_sub_i32 s5, s4, s5
	s_and_b32 s5, s5, 0xff
	v_mov_b32_e32 v68, v32
	s_waitcnt lgkmcnt(0)
	v_mov_b32_e32 v69, v49
	v_mov_b32_e32 v49, v33
	v_mov_b32_e32 v32, v34
	v_mov_b32_e32 v33, v51
	s_cmp_eq_u32 s5, 2
	v_pk_mul_f32 v[70:71], v[48:49], v[130:131]
	v_pk_mul_f32 v[48:49], v[32:33], v[130:131]
	v_mov_b32_e32 v51, v35
	v_mov_b32_e32 v32, v40
	v_mov_b32_e32 v33, v57
	v_mov_b32_e32 v57, v41
	v_mul_f32_e32 v40, v42, v130
	v_mov_b32_e32 v42, v59
	s_cselect_b64 s[34:35], -1, 0
	s_cmp_lg_u32 s5, 2
	v_pk_mul_f32 v[68:69], v[68:69], v[130:131]
	v_pk_mul_f32 v[50:51], v[50:51], v[130:131]
	v_pk_mul_f32 v[32:33], v[32:33], v[130:131]
	v_pk_mul_f32 v[34:35], v[56:57], v[130:131]
	v_mul_f32_e32 v56, v58, v130
	v_pk_mul_f32 v[42:43], v[42:43], v[130:131]
	s_cbranch_scc1 .LBB0_616
	v_mov_b32_e32 v72, v206
	v_mov_b32_e32 v73, v207
	v_mov_b32_e32 v74, v208
	v_mov_b32_e32 v75, v209
	v_mov_b32_e32 v76, v210
	v_mov_b32_e32 v77, v211
	v_mov_b32_e32 v78, v212
	v_mov_b32_e32 v79, v213
	v_mov_b32_e32 v80, v214
	v_mov_b32_e32 v81, v215
	v_mov_b32_e32 v82, v216
	v_mov_b32_e32 v83, v217
	v_mov_b32_e32 v84, v218
	v_mov_b32_e32 v85, v219
	v_mov_b32_e32 v86, v220
	v_mov_b32_e32 v87, v221
	v_mov_b32_e32 v88, v70
	v_mov_b32_e32 v89, v69
	v_mov_b32_e32 v92, v50
	v_mov_b32_e32 v93, v49
	v_mov_b32_e32 v100, v34
	v_mov_b32_e32 v101, v33
	v_mov_b32_e32 v58, v68
	v_mov_b32_e32 v59, v71
	v_mov_b32_e32 v90, v48
	v_mov_b32_e32 v91, v51
	v_mov_b32_e32 v94, v32
	v_mov_b32_e32 v95, v35
	v_mov_b32_e32 v106, v73
	v_mov_b32_e32 v107, v75
	v_mov_b32_e32 v108, v73
	v_mov_b32_e32 v73, v75
	v_mov_b32_e32 v110, v77
	v_mov_b32_e32 v111, v79
	v_mov_b32_e32 v112, v77
	v_mov_b32_e32 v77, v79
	v_mov_b32_e32 v79, v82
	v_mov_b32_e32 v114, v81
	v_mov_b32_e32 v115, v83
	v_mov_b32_e32 v116, v81
	v_mov_b32_e32 v117, v82
	v_mov_b32_e32 v81, v83
	v_mul_f32_e32 v82, v40, v84
	v_mul_f32_e32 v118, v56, v85
	v_mul_f32_e32 v56, v56, v84
	v_mul_f32_e32 v84, v40, v85
	v_pk_mul_f32 v[40:41], v[42:43], v[86:87] op_sel:[1,0] op_sel_hi:[0,1]
	v_pk_mul_f32 v[42:43], v[42:43], v[86:87]
	v_mov_b32_e32 v102, v72
	v_mov_b32_e32 v103, v74
	v_mov_b32_e32 v109, v74
	v_mov_b32_e32 v74, v76
	v_mov_b32_e32 v75, v78
	v_mov_b32_e32 v113, v78
	v_mov_b32_e32 v78, v80
	v_pk_mul_f32 v[86:87], v[88:89], v[106:107]
	v_pk_mul_f32 v[70:71], v[70:71], v[72:73]
	v_pk_mul_f32 v[72:73], v[92:93], v[110:111]
	v_pk_mul_f32 v[50:51], v[50:51], v[76:77]
	v_pk_mul_f32 v[76:77], v[100:101], v[114:115]
	v_pk_mul_f32 v[34:35], v[34:35], v[80:81]
	v_mov_b32_e32 v83, v40
	v_mov_b32_e32 v119, v41
	v_mov_b32_e32 v57, v42
	v_mov_b32_e32 v85, v43
	v_pk_fma_f32 v[58:59], v[58:59], v[102:103], v[86:87] neg_lo:[0,0,1] neg_hi:[0,0,1]
	v_pk_fma_f32 v[72:73], v[90:91], v[74:75], v[72:73] neg_lo:[0,0,1] neg_hi:[0,0,1]
	v_pk_fma_f32 v[74:75], v[94:95], v[78:79], v[76:77] neg_lo:[0,0,1] neg_hi:[0,0,1]
	v_pk_add_f32 v[40:41], v[82:83], v[118:119] neg_lo:[0,1] neg_hi:[0,1]
	v_pk_fma_f32 v[70:71], v[68:69], v[108:109], v[70:71]
	v_pk_fma_f32 v[50:51], v[48:49], v[112:113], v[50:51]
	v_pk_fma_f32 v[34:35], v[32:33], v[116:117], v[34:35]
	v_pk_add_f32 v[56:57], v[56:57], v[84:85]
	v_mov_b32_e32 v69, v71
	v_mov_b32_e32 v49, v51
	v_mov_b32_e32 v33, v35
	v_mov_b32_e32 v42, v57
	v_mov_b32_e32 v68, v58
	v_mov_b32_e32 v71, v59
	v_mov_b32_e32 v48, v72
	v_mov_b32_e32 v51, v73
	v_mov_b32_e32 v32, v74
	v_mov_b32_e32 v35, v75
	v_mov_b32_e32 v43, v41
.LBB0_616:
	s_lshl_b32 s4, s4, 7
	s_add_u32 s4, s65, s4
	s_addc_u32 s5, s68, 0
	v_mov_b32_e32 v58, v36
	v_mov_b32_e32 v59, v53
	v_mov_b32_e32 v53, v37
	v_mov_b32_e32 v36, v38
	v_mov_b32_e32 v37, v55
	v_lshl_add_u64 v[74:75], s[4:5], 0, v[128:129]
	v_pk_mul_f32 v[72:73], v[52:53], v[130:131]
	v_pk_mul_f32 v[52:53], v[36:37], v[130:131]
	v_mov_b32_e32 v55, v39
	v_mov_b32_e32 v36, v44
	v_mov_b32_e32 v37, v61
	v_mov_b32_e32 v61, v45
	v_mul_f32_e32 v44, v46, v130
	v_mov_b32_e32 v46, v63
	v_cndmask_b32_e64 v41, 0, 1, s[34:35]
	v_lshl_add_u64 v[76:77], v[104:105], 1, v[74:75]
	v_cvt_pk_bf16_f32 v78, v68, v71
	v_cvt_pk_bf16_f32 v79, v48, v51
	v_cvt_pk_bf16_f32 v80, v32, v35
	v_cvt_pk_bf16_f32 v81, v40, v43
	v_pk_mul_f32 v[58:59], v[58:59], v[130:131]
	v_pk_mul_f32 v[54:55], v[54:55], v[130:131]
	v_pk_mul_f32 v[36:37], v[36:37], v[130:131]
	v_pk_mul_f32 v[38:39], v[60:61], v[130:131]
	v_mul_f32_e32 v60, v62, v130
	v_cmp_ne_u32_e64 s[4:5], 1, v41
	s_andn2_b64 vcc, exec, s[34:35]
	v_pk_mul_f32 v[46:47], v[46:47], v[130:131]
	v_cvt_pk_bf16_f32 v82, v70, v69
	v_cvt_pk_bf16_f32 v83, v50, v49
	v_cvt_pk_bf16_f32 v84, v34, v33
	v_cvt_pk_bf16_f32 v85, v56, v42
	global_store_dwordx4 v[76:77], v[78:81], off
	global_store_dwordx4 v[76:77], v[82:85], off offset:64
	s_cbranch_vccnz .LBB0_618
	v_mov_b32_e32 v78, v222
	v_mov_b32_e32 v79, v223
	v_mov_b32_e32 v80, v224
	v_mov_b32_e32 v81, v225
	v_mov_b32_e32 v82, v226
	v_mov_b32_e32 v83, v227
	v_mov_b32_e32 v84, v228
	v_mov_b32_e32 v85, v229
	v_mov_b32_e32 v86, v230
	v_mov_b32_e32 v87, v231
	v_mov_b32_e32 v88, v232
	v_mov_b32_e32 v89, v233
	v_mov_b32_e32 v90, v234
	v_mov_b32_e32 v91, v235
	v_mov_b32_e32 v92, v254
	v_mov_b32_e32 v93, v255
	v_mov_b32_e32 v94, v72
	v_mov_b32_e32 v95, v59
	v_mov_b32_e32 v100, v54
	v_mov_b32_e32 v101, v53
	v_mov_b32_e32 v104, v38
	v_mov_b32_e32 v105, v37
	v_mov_b32_e32 v62, v58
	v_mov_b32_e32 v63, v73
	v_mov_b32_e32 v96, v52
	v_mov_b32_e32 v97, v55
	v_mov_b32_e32 v102, v36
	v_mov_b32_e32 v103, v39
	v_mov_b32_e32 v108, v79
	v_mov_b32_e32 v109, v81
	v_mov_b32_e32 v110, v79
	v_mov_b32_e32 v79, v81
	v_mov_b32_e32 v112, v83
	v_mov_b32_e32 v113, v85
	v_mov_b32_e32 v114, v83
	v_mov_b32_e32 v83, v85
	v_mov_b32_e32 v85, v88
	v_mov_b32_e32 v116, v87
	v_mov_b32_e32 v117, v89
	v_mov_b32_e32 v118, v87
	v_mov_b32_e32 v119, v88
	v_mov_b32_e32 v87, v89
	v_mul_f32_e32 v88, v44, v90
	v_mul_f32_e32 v120, v60, v91
	v_mul_f32_e32 v60, v60, v90
	v_mul_f32_e32 v90, v44, v91
	v_pk_mul_f32 v[44:45], v[46:47], v[92:93] op_sel:[1,0] op_sel_hi:[0,1]
	v_pk_mul_f32 v[46:47], v[46:47], v[92:93]
	v_mov_b32_e32 v106, v78
	v_mov_b32_e32 v107, v80
	v_mov_b32_e32 v111, v80
	v_mov_b32_e32 v80, v82
	v_mov_b32_e32 v81, v84
	v_mov_b32_e32 v115, v84
	v_mov_b32_e32 v84, v86
	v_pk_mul_f32 v[92:93], v[94:95], v[108:109]
	v_pk_mul_f32 v[72:73], v[72:73], v[78:79]
	v_pk_mul_f32 v[78:79], v[100:101], v[112:113]
	v_pk_mul_f32 v[54:55], v[54:55], v[82:83]
	v_pk_mul_f32 v[82:83], v[104:105], v[116:117]
	v_pk_mul_f32 v[38:39], v[38:39], v[86:87]
	v_mov_b32_e32 v89, v44
	v_mov_b32_e32 v121, v45
	v_mov_b32_e32 v61, v46
	v_mov_b32_e32 v91, v47
	v_pk_fma_f32 v[62:63], v[62:63], v[106:107], v[92:93] neg_lo:[0,0,1] neg_hi:[0,0,1]
	v_pk_fma_f32 v[78:79], v[96:97], v[80:81], v[78:79] neg_lo:[0,0,1] neg_hi:[0,0,1]
	v_pk_fma_f32 v[80:81], v[102:103], v[84:85], v[82:83] neg_lo:[0,0,1] neg_hi:[0,0,1]
	v_pk_add_f32 v[44:45], v[88:89], v[120:121] neg_lo:[0,1] neg_hi:[0,1]
	v_pk_fma_f32 v[72:73], v[58:59], v[110:111], v[72:73]
	v_pk_fma_f32 v[54:55], v[52:53], v[114:115], v[54:55]
	v_pk_fma_f32 v[38:39], v[36:37], v[118:119], v[38:39]
	v_pk_add_f32 v[60:61], v[60:61], v[90:91]
	v_mov_b32_e32 v59, v73
	v_mov_b32_e32 v53, v55
	v_mov_b32_e32 v37, v39
	v_mov_b32_e32 v46, v61
	v_mov_b32_e32 v58, v62
	v_mov_b32_e32 v73, v63
	v_mov_b32_e32 v52, v78
	v_mov_b32_e32 v55, v79
	v_mov_b32_e32 v36, v80
	v_mov_b32_e32 v39, v81
	v_mov_b32_e32 v47, v45
.LBB0_618:
	v_cvt_pk_bf16_f32 v78, v58, v73
	v_cvt_pk_bf16_f32 v79, v52, v55
	v_cvt_pk_bf16_f32 v80, v36, v39
	v_cvt_pk_bf16_f32 v81, v44, v47
	v_mov_b32_e32 v62, v0
	v_mov_b32_e32 v63, v17
	v_mov_b32_e32 v17, v1
	v_mov_b32_e32 v0, v2
	v_mov_b32_e32 v1, v19
	v_cvt_pk_bf16_f32 v82, v72, v59
	v_cvt_pk_bf16_f32 v83, v54, v53
	v_cvt_pk_bf16_f32 v84, v38, v37
	v_cvt_pk_bf16_f32 v85, v60, v46
	global_store_dwordx4 v[76:77], v[78:81], off offset:32
	global_store_dwordx4 v[76:77], v[82:85], off offset:96
	v_pk_mul_f32 v[76:77], v[16:17], v[98:99]
	v_pk_mul_f32 v[16:17], v[0:1], v[98:99]
	v_mov_b32_e32 v19, v3
	v_mov_b32_e32 v0, v8
	v_mov_b32_e32 v1, v25
	v_mov_b32_e32 v25, v9
	v_mul_f32_e32 v8, v10, v98
	v_mov_b32_e32 v10, v27
	v_pk_mul_f32 v[62:63], v[62:63], v[98:99]
	v_pk_mul_f32 v[18:19], v[18:19], v[98:99]
	v_pk_mul_f32 v[0:1], v[0:1], v[98:99]
	v_pk_mul_f32 v[2:3], v[24:25], v[98:99]
	v_mul_f32_e32 v24, v26, v98
	s_and_b64 vcc, exec, s[4:5]
	v_pk_mul_f32 v[10:11], v[10:11], v[98:99]
	s_cbranch_vccnz .LBB0_620
	v_mov_b32_e32 v78, v238
	v_mov_b32_e32 v79, v239
	v_mov_b32_e32 v80, v240
	v_mov_b32_e32 v81, v241
	v_mov_b32_e32 v82, v242
	v_mov_b32_e32 v83, v243
	v_mov_b32_e32 v84, v244
	v_mov_b32_e32 v85, v245
	v_mov_b32_e32 v86, v246
	v_mov_b32_e32 v87, v247
	v_mov_b32_e32 v88, v248
	v_mov_b32_e32 v89, v249
	v_mov_b32_e32 v90, v250
	v_mov_b32_e32 v91, v251
	v_mov_b32_e32 v92, v252
	v_mov_b32_e32 v93, v253
	v_mov_b32_e32 v94, v76
	v_mov_b32_e32 v95, v63
	v_mov_b32_e32 v100, v18
	v_mov_b32_e32 v101, v17
	v_mov_b32_e32 v104, v2
	v_mov_b32_e32 v105, v1
	v_mov_b32_e32 v26, v62
	v_mov_b32_e32 v27, v77
	v_mov_b32_e32 v96, v16
	v_mov_b32_e32 v97, v19
	v_mov_b32_e32 v102, v0
	v_mov_b32_e32 v103, v3
	v_mov_b32_e32 v108, v79
	v_mov_b32_e32 v109, v81
	v_mov_b32_e32 v110, v79
	v_mov_b32_e32 v79, v81
	v_mov_b32_e32 v112, v83
	v_mov_b32_e32 v113, v85
	v_mov_b32_e32 v114, v83
	v_mov_b32_e32 v83, v85
	v_mov_b32_e32 v85, v88
	v_mov_b32_e32 v116, v87
	v_mov_b32_e32 v117, v89
	v_mov_b32_e32 v118, v87
	v_mov_b32_e32 v119, v88
	v_mov_b32_e32 v87, v89
	v_mul_f32_e32 v88, v8, v90
	v_mul_f32_e32 v120, v24, v91
	v_mul_f32_e32 v24, v24, v90
	v_mul_f32_e32 v90, v8, v91
	v_pk_mul_f32 v[8:9], v[10:11], v[92:93] op_sel:[1,0] op_sel_hi:[0,1]
	v_pk_mul_f32 v[10:11], v[10:11], v[92:93]
	v_mov_b32_e32 v106, v78
	v_mov_b32_e32 v107, v80
	v_mov_b32_e32 v111, v80
	v_mov_b32_e32 v80, v82
	v_mov_b32_e32 v81, v84
	v_mov_b32_e32 v115, v84
	v_mov_b32_e32 v84, v86
	v_pk_mul_f32 v[92:93], v[94:95], v[108:109]
	v_pk_mul_f32 v[76:77], v[76:77], v[78:79]
	v_pk_mul_f32 v[78:79], v[100:101], v[112:113]
	v_pk_mul_f32 v[18:19], v[18:19], v[82:83]
	v_pk_mul_f32 v[82:83], v[104:105], v[116:117]
	v_pk_mul_f32 v[2:3], v[2:3], v[86:87]
	v_mov_b32_e32 v89, v8
	v_mov_b32_e32 v121, v9
	v_mov_b32_e32 v25, v10
	v_mov_b32_e32 v91, v11
	v_pk_fma_f32 v[26:27], v[26:27], v[106:107], v[92:93] neg_lo:[0,0,1] neg_hi:[0,0,1]
	v_pk_fma_f32 v[78:79], v[96:97], v[80:81], v[78:79] neg_lo:[0,0,1] neg_hi:[0,0,1]
	v_pk_fma_f32 v[80:81], v[102:103], v[84:85], v[82:83] neg_lo:[0,0,1] neg_hi:[0,0,1]
	v_pk_add_f32 v[8:9], v[88:89], v[120:121] neg_lo:[0,1] neg_hi:[0,1]
	v_pk_fma_f32 v[76:77], v[62:63], v[110:111], v[76:77]
	v_pk_fma_f32 v[18:19], v[16:17], v[114:115], v[18:19]
	v_pk_fma_f32 v[2:3], v[0:1], v[118:119], v[2:3]
	v_pk_add_f32 v[24:25], v[24:25], v[90:91]
	v_mov_b32_e32 v63, v77
	v_mov_b32_e32 v17, v19
	v_mov_b32_e32 v1, v3
	v_mov_b32_e32 v10, v25
	v_mov_b32_e32 v62, v26
	v_mov_b32_e32 v77, v27
	v_mov_b32_e32 v16, v78
	v_mov_b32_e32 v19, v79
	v_mov_b32_e32 v0, v80
	v_mov_b32_e32 v3, v81
	v_mov_b32_e32 v11, v9

.LBB0_629:
	s_and_b32 s2, s66, 0x700
	s_or_b32 s58, s2, s14
	s_movk_i32 s2, 0x100
	v_mov_b32 v0, v144
	s_waitcnt lgkmcnt(0)
	v_readfirstlane_b32 s4, v0
	v_cmp_gt_i32_e32 vcc, s2, v0
	s_barrier
	s_and_saveexec_b64 s[2:3], vcc
	s_cbranch_execz .LBB0_631
	v_add_u32_e32 v1, s58, v0
	v_add_u32_e32 v2, 0xc000, v1
	v_ashrrev_i32_e32 v3, 31, v2
	v_lshl_add_u64 v[2:3], v[2:3], 2, s[0:1]
	global_load_dword v238, v[2:3], off
.LBB0_631:
	s_or_b64 exec, exec, s[2:3]
	s_lshr_b32 s2, s69, 3
	s_ashr_i32 s3, s4, 6
	s_mul_i32 s5, s58, 0xe00
	s_add_u32 s70, s61, s5
	s_addc_u32 s71, s62, 0
	s_lshl_b32 s6, s2, 8
	s_lshl_b64 s[72:73], s[6:7], 7
	s_add_u32 s72, s27, s72
	s_addc_u32 s73, s60, s73
	s_lshl_b32 s5, s3, 2
	v_and_b32_e32 v1, 7, v0
	v_bfe_u32 v2, v0, 4, 2
	s_and_b32 s5, s5, 4
	v_bitop3_b32 v1, s5, v1, v2 bitop3:0x36
	v_bfe_u32 v2, v0, 3, 3
	v_lshl_or_b32 v2, s3, 3, v2
	v_ashrrev_i32_e32 v3, 31, v2
	v_mov_b64_e32 v[4:5], s[70:71]
	s_movk_i32 s5, 0xe00
	s_lshl_b32 s78, s3, 10
	v_mad_i64_i32 v[4:5], s[70:71], v2, s5, v[4:5]
	v_lshlrev_b32_e32 v128, 4, v1
	v_lshlrev_b64 v[2:3], 7, v[2:3]
	s_add_i32 s80, s78, 0
	v_lshl_add_u64 v[130:131], v[4:5], 0, v[128:129]
	v_lshl_add_u64 v[2:3], s[72:73], 0, v[2:3]
	s_mov_b32 m0, s80
	s_mov_b64 s[70:71], 0x38000
	s_add_i32 s79, s80, 0x2000
	v_lshl_add_u64 v[132:133], v[2:3], 0, v[128:129]
	global_load_lds_dwordx4 v[130:131], off
	v_lshl_add_u64 v[2:3], v[130:131], 0, s[70:71]
	s_mov_b32 m0, s79
	s_mov_b64 s[70:71], 0x70000
	s_add_i32 s76, s80, 0x4000
	global_load_lds_dwordx4 v[2:3], off
	v_lshl_add_u64 v[2:3], v[130:131], 0, s[70:71]
	s_mov_b32 m0, s76
	s_mov_b64 s[70:71], 0xa8000
	s_add_i32 s77, s80, 0x6000
	global_load_lds_dwordx4 v[2:3], off
	v_lshl_add_u64 v[2:3], v[130:131], 0, s[70:71]
	s_mov_b32 m0, s77
	s_mov_b64 s[70:71], 0x2000
	global_load_lds_dwordx4 v[2:3], off
	s_add_i32 m0, s80, 0x10000
	v_lshl_add_u64 v[2:3], v[132:133], 0, s[70:71]
	global_load_lds_dwordx4 v[132:133], off
	s_add_i32 m0, s80, 0x12000
	s_mov_b64 s[70:71], 0x4000
	global_load_lds_dwordx4 v[2:3], off
	v_lshl_add_u64 v[2:3], v[132:133], 0, s[70:71]
	s_add_i32 m0, s80, 0x14000
	s_mov_b64 s[70:71], 0x6000
	global_load_lds_dwordx4 v[2:3], off
	v_lshl_add_u64 v[2:3], v[132:133], 0, s[70:71]
	s_add_i32 m0, s80, 0x16000
	s_cmp_lt_i32 s3, 4
	global_load_lds_dwordx4 v[2:3], off
	v_cmp_gt_i32_e32 vcc, 0x100, v144
	s_and_saveexec_b64 s[98:99], vcc
	s_cbranch_execz .Lrs_skip2
	s_waitcnt vmcnt(0)
	v_fmamk_f32 v238, v238, 0x3b800000, v138
	v_mul_f32_e32 v239, 0x4b800000, v238
	v_cmp_gt_f32_e32 vcc, 0x800000, v238
	s_nop 1
	v_cndmask_b32_e32 v238, v238, v239, vcc
	v_rsq_f32_e32 v238, v238
	v_lshl_add_u32 v239, v144, 2, 0
	v_add_u32_e32 v239, 0x20000, v239
	v_mul_f32_e32 v240, 0x45800000, v238
	v_cndmask_b32_e32 v238, v238, v240, vcc
	ds_write_b32 v239, v238

.LBB0_666:
	s_or_b64 exec, exec, s[2:3]
	s_add_i32 s2, s67, s69
	s_ashr_i32 s2, s2, 3
	s_ashr_i32 s3, s4, 6
	s_mul_i32 s5, s58, 0xe00
	s_add_u32 s70, s61, s5
	s_addc_u32 s71, s62, 0
	s_lshl_b32 s72, s2, 8
	s_ashr_i32 s73, s72, 31
	s_lshl_b64 s[72:73], s[72:73], 7
	s_add_u32 s72, s27, s72
	s_addc_u32 s73, s60, s73
	s_lshl_b32 s5, s3, 2
	v_and_b32_e32 v1, 7, v0
	v_bfe_u32 v2, v0, 4, 2
	s_and_b32 s5, s5, 4
	v_bitop3_b32 v1, s5, v1, v2 bitop3:0x36
	v_bfe_u32 v2, v0, 3, 3
	v_lshl_or_b32 v2, s3, 3, v2
	v_ashrrev_i32_e32 v3, 31, v2
	v_mov_b64_e32 v[4:5], s[70:71]
	s_movk_i32 s5, 0xe00
	s_lshl_b32 s79, s3, 10
	v_mad_i64_i32 v[4:5], s[70:71], v2, s5, v[4:5]
	v_lshlrev_b32_e32 v128, 4, v1
	v_lshlrev_b64 v[2:3], 7, v[2:3]
	s_add_i32 s81, s79, 0
	v_lshl_add_u64 v[130:131], v[4:5], 0, v[128:129]
	v_lshl_add_u64 v[2:3], s[72:73], 0, v[2:3]
	s_mov_b32 m0, s81
	s_mov_b64 s[70:71], 0x38000
	s_add_i32 s80, s81, 0x2000
	v_lshl_add_u64 v[132:133], v[2:3], 0, v[128:129]
	global_load_lds_dwordx4 v[130:131], off
	v_lshl_add_u64 v[2:3], v[130:131], 0, s[70:71]
	s_mov_b32 m0, s80
	s_mov_b64 s[70:71], 0x70000
	s_add_i32 s77, s81, 0x4000
	global_load_lds_dwordx4 v[2:3], off
	v_lshl_add_u64 v[2:3], v[130:131], 0, s[70:71]
	s_mov_b32 m0, s77
	s_mov_b64 s[70:71], 0xa8000
	s_add_i32 s78, s81, 0x6000
	global_load_lds_dwordx4 v[2:3], off
	v_lshl_add_u64 v[2:3], v[130:131], 0, s[70:71]
	s_mov_b32 m0, s78
	s_mov_b64 s[70:71], 0x2000
	global_load_lds_dwordx4 v[2:3], off
	s_add_i32 m0, s81, 0x10000
	v_lshl_add_u64 v[2:3], v[132:133], 0, s[70:71]
	global_load_lds_dwordx4 v[132:133], off
	s_add_i32 m0, s81, 0x12000
	s_mov_b64 s[70:71], 0x4000
	global_load_lds_dwordx4 v[2:3], off
	v_lshl_add_u64 v[2:3], v[132:133], 0, s[70:71]
	s_add_i32 m0, s81, 0x14000
	s_mov_b64 s[70:71], 0x6000
	global_load_lds_dwordx4 v[2:3], off
	v_lshl_add_u64 v[2:3], v[132:133], 0, s[70:71]
	s_add_i32 m0, s81, 0x16000
	s_cmp_lt_i32 s3, 4
	global_load_lds_dwordx4 v[2:3], off
	v_cmp_gt_i32_e32 vcc, 0x100, v144
	s_and_saveexec_b64 s[98:99], vcc
	s_cbranch_execz .Lrs_skip1
	s_waitcnt vmcnt(0)
	v_fmamk_f32 v238, v238, 0x3b800000, v138
	v_mul_f32_e32 v239, 0x4b800000, v238
	v_cmp_gt_f32_e32 vcc, 0x800000, v238
	s_nop 1
	v_cndmask_b32_e32 v238, v238, v239, vcc
	v_rsq_f32_e32 v238, v238
	v_lshl_add_u32 v239, v144, 2, 0
	v_add_u32_e32 v239, 0x20000, v239
	v_mul_f32_e32 v240, 0x45800000, v238
	v_cndmask_b32_e32 v238, v238, v240, vcc
	ds_write_b32 v239, v238

.LBB0_694:
	s_and_b64 vcc, exec, s[0:1]
	s_cbranch_vccz .LBB0_725
	v_readlane_b32 s0, v237, 20
	s_lshl_b32 s1, s26, 8
	s_lshl_b32 s0, s0, 11
	s_and_b32 s1, s1, 0x700
	s_or_b32 s6, s1, s0
	s_movk_i32 s0, 0x100
	v_mov_b32 v0, v144
	s_waitcnt lgkmcnt(0)
	v_readfirstlane_b32 s3, v0
	v_cmp_gt_i32_e32 vcc, s0, v0
	s_barrier
	s_and_saveexec_b64 s[0:1], vcc
	s_cbranch_execz .LBB0_697
	v_add_u32_e32 v1, s6, v0
	v_add_u32_e32 v2, 0xc000, v1
	v_ashrrev_i32_e32 v3, 31, v2
	v_lshl_add_u64 v[2:3], v[2:3], 2, s[28:29]
	v_add_co_u32_e32 v2, vcc, 0x40000, v2
	s_mov_b32 s2, 0x800000
	s_nop 0
	v_addc_co_u32_e32 v3, vcc, 0, v3, vcc
	global_load_dword v238, v[2:3], off
.LBB0_697:
	s_or_b64 exec, exec, s[0:1]
	s_lshr_b32 s0, s94, 6
	s_or_b32 s2, s0, 6
	s_ashr_i32 s0, s3, 6
	s_mul_i32 s4, s6, 0xe00
	s_add_u32 s4, s61, s4
	s_addc_u32 s5, s62, 0
	s_lshl_b32 s7, s2, 15
	s_add_u32 s8, s27, s7
	s_addc_u32 s9, s60, 0
	s_lshl_b32 s7, s0, 2
	v_and_b32_e32 v1, 7, v0
	v_bfe_u32 v2, v0, 4, 2
	s_and_b32 s7, s7, 4
	v_bitop3_b32 v1, s7, v1, v2 bitop3:0x36
	v_bfe_u32 v2, v0, 3, 3
	v_lshl_or_b32 v2, s0, 3, v2
	s_movk_i32 s1, 0xe00
	v_ashrrev_i32_e32 v3, 31, v2
	v_mov_b64_e32 v[4:5], s[4:5]
	s_lshl_b32 s15, s0, 10
	v_mad_i64_i32 v[4:5], s[4:5], v2, s1, v[4:5]
	v_lshlrev_b32_e32 v6, 4, v1
	v_mov_b32_e32 v7, 0
	v_lshlrev_b64 v[2:3], 7, v[2:3]
	s_add_i32 s17, s15, 0
	v_lshl_add_u64 v[130:131], v[4:5], 0, v[6:7]
	v_lshl_add_u64 v[2:3], s[8:9], 0, v[2:3]
	s_mov_b32 m0, s17
	s_mov_b64 s[4:5], 0x38000
	s_add_i32 s16, s17, 0x2000
	v_lshl_add_u64 v[128:129], v[2:3], 0, v[6:7]
	global_load_lds_dwordx4 v[130:131], off
	v_lshl_add_u64 v[2:3], v[130:131], 0, s[4:5]
	s_mov_b32 m0, s16
	s_mov_b64 s[4:5], 0x70000
	s_add_i32 s13, s17, 0x4000
	global_load_lds_dwordx4 v[2:3], off
	v_lshl_add_u64 v[2:3], v[130:131], 0, s[4:5]
	s_mov_b32 m0, s13
	s_mov_b64 s[4:5], 0xa8000
	s_add_i32 s14, s17, 0x6000
	global_load_lds_dwordx4 v[2:3], off
	v_lshl_add_u64 v[2:3], v[130:131], 0, s[4:5]
	s_mov_b32 m0, s14
	s_mov_b64 s[4:5], 0x2000
	global_load_lds_dwordx4 v[2:3], off
	s_add_i32 m0, s17, 0x10000
	v_lshl_add_u64 v[2:3], v[128:129], 0, s[4:5]
	global_load_lds_dwordx4 v[128:129], off
	s_add_i32 m0, s17, 0x12000
	s_mov_b64 s[4:5], 0x4000
	global_load_lds_dwordx4 v[2:3], off
	v_lshl_add_u64 v[2:3], v[128:129], 0, s[4:5]
	s_add_i32 m0, s17, 0x14000
	s_mov_b64 s[4:5], 0x6000
	global_load_lds_dwordx4 v[2:3], off
	v_lshl_add_u64 v[2:3], v[128:129], 0, s[4:5]
	s_add_i32 m0, s17, 0x16000
	v_and_b32_e32 v136, 63, v0
	global_load_lds_dwordx4 v[2:3], off
	v_cmp_gt_i32_e32 vcc, 0x100, v144
	s_and_saveexec_b64 s[98:99], vcc
	s_cbranch_execz .Lrs_skip0
	s_waitcnt vmcnt(0)
	v_mov_b32_e32 v239, 0x358637bd
	v_fmac_f32_e32 v239, 0x3b800000, v238
	v_mul_f32_e32 v238, 0x4b800000, v239
	v_cmp_gt_f32_e32 vcc, 0x800000, v239
	s_nop 1
	v_cndmask_b32_e32 v238, v239, v238, vcc
	v_rsq_f32_e32 v238, v238
	v_lshl_add_u32 v239, v144, 2, 0
	v_add_u32_e32 v239, 0x20000, v239
	v_mul_f32_e32 v240, 0x45800000, v238
	v_cndmask_b32_e32 v238, v238, v240, vcc
	ds_write_b32 v239, v238
.Lrs_skip0:
	s_or_b64 exec, exec, s[98:99]
	s_waitcnt vmcnt(0)
	s_barrier
	s_cmp_lt_i32 s0, 4
	s_cbranch_scc1 .LBB0_699
	s_barrier

	.amdhsa_kernel _Z4mega6Params
		.amdhsa_group_segment_fixed_size 0
		.amdhsa_private_segment_fixed_size 0
		.amdhsa_kernarg_size 456
		.amdhsa_user_sgpr_count 2
		.amdhsa_user_sgpr_dispatch_ptr 0
		.amdhsa_user_sgpr_queue_ptr 0
		.amdhsa_user_sgpr_kernarg_segment_ptr 1
		.amdhsa_user_sgpr_dispatch_id 0
		.amdhsa_user_sgpr_kernarg_preload_length 0
		.amdhsa_user_sgpr_kernarg_preload_offset 0
		.amdhsa_user_sgpr_private_segment_size 0
		.amdhsa_uses_dynamic_stack 0
		.amdhsa_enable_private_segment 0
		.amdhsa_system_sgpr_workgroup_id_x 1
		.amdhsa_system_sgpr_workgroup_id_y 0
		.amdhsa_system_sgpr_workgroup_id_z 0
		.amdhsa_system_sgpr_workgroup_info 0
		.amdhsa_system_vgpr_workitem_id 2
		.amdhsa_next_free_vgpr 256
		.amdhsa_next_free_sgpr 102
		.amdhsa_accum_offset 256
		.amdhsa_reserve_vcc 1
		.amdhsa_float_round_mode_32 0
		.amdhsa_float_round_mode_16_64 0
		.amdhsa_float_denorm_mode_32 3
		.amdhsa_float_denorm_mode_16_64 3
		.amdhsa_dx10_clamp 1
		.amdhsa_ieee_mode 1
		.amdhsa_fp16_overflow 0
		.amdhsa_tg_split 0
		.amdhsa_exception_fp_ieee_invalid_op 0
		.amdhsa_exception_fp_denorm_src 0
		.amdhsa_exception_fp_ieee_div_zero 0
		.amdhsa_exception_fp_ieee_overflow 0
		.amdhsa_exception_fp_ieee_underflow 0
		.amdhsa_exception_fp_ieee_inexact 0
		.amdhsa_exception_int_div_zero 0
	.end_amdhsa_kernel

amdhsa.kernels:
  - .agpr_count:     0
    .args:
      - .offset:         0
        .size:           200
        .value_kind:     by_value
      - .offset:         200
        .size:           4
        .value_kind:     hidden_block_count_x
      - .offset:         204
        .size:           4
        .value_kind:     hidden_block_count_y
      - .offset:         208
        .size:           4
        .value_kind:     hidden_block_count_z
      - .offset:         212
        .size:           2
        .value_kind:     hidden_group_size_x
      - .offset:         214
        .size:           2
        .value_kind:     hidden_group_size_y
      - .offset:         216
        .size:           2
        .value_kind:     hidden_group_size_z
      - .offset:         218
        .size:           2
        .value_kind:     hidden_remainder_x
      - .offset:         220
        .size:           2
        .value_kind:     hidden_remainder_y
      - .offset:         222
        .size:           2
        .value_kind:     hidden_remainder_z
      - .offset:         240
        .size:           8
        .value_kind:     hidden_global_offset_x
      - .offset:         248
        .size:           8
        .value_kind:     hidden_global_offset_y
      - .offset:         256
        .size:           8
        .value_kind:     hidden_global_offset_z
      - .offset:         264
        .size:           2
        .value_kind:     hidden_grid_dims
      - .offset:         288
        .size:           8
        .value_kind:     hidden_multigrid_sync_arg
      - .offset:         320
        .size:           4
        .value_kind:     hidden_dynamic_lds_size
    .group_segment_fixed_size: 0
    .kernarg_segment_align: 8
    .kernarg_segment_size: 456
    .language:       OpenCL C
    .language_version:
      - 2
      - 0
    .max_flat_workgroup_size: 512
    .name:           _Z4mega6Params
    .private_segment_fixed_size: 0
    .sgpr_count:     108
    .sgpr_spill_count: 28
    .symbol:         _Z4mega6Params.kd
    .uniform_work_group_size: 1
    .uses_dynamic_stack: false
    .vgpr_count:     256
    .vgpr_spill_count: 0
    .wavefront_size: 64
